# GEMM K-loops: one static s_setprio 1 for the trailing wave half (wr=1) at phase entry instead of per-MFMA-block priority toggles; reset at phase exit (on v93)
# speedup vs baseline: 1.0032x; 1.0032x over previous
.LBB0_75:
	s_andn2_b64 vcc, exec, s[6:7]
	s_mov_b32 s48, s66
	s_cbranch_vccnz .LBB0_192
	v_ashrrev_i32_e32 v3, 31, v1
	v_lshrrev_b32_e32 v3, 26, v3
	v_add_u32_e32 v3, v1, v3
	v_ashrrev_i32_e32 v10, 6, v3
	v_bfe_i32 v3, v1, 27, 1
	s_waitcnt lgkmcnt(0)
	v_lshlrev_b32_e32 v2, 4, v1
	v_lshrrev_b32_e32 v3, 22, v3
	v_add_u32_e32 v3, v2, v3
	v_and_b32_e32 v3, 0xfffffc00, v3
	v_sub_u32_e32 v3, v2, v3
	v_lshrrev_b32_e32 v4, 4, v3
	v_bitop3_b32 v3, v4, v3, 32 bitop3:0x6c
	v_ashrrev_i32_e32 v5, 31, v3
	v_readlane_b32 s6, v254, 57
	v_lshrrev_b32_e32 v5, 26, v5
	v_readlane_b32 s7, v254, 58
	v_add_u32_e32 v5, v3, v5
	s_and_b64 s[6:7], s[6:7], exec
	v_lshlrev_b32_e32 v4, 3, v10
	v_ashrrev_i32_e32 v11, 6, v5
	v_and_b32_e32 v5, 0xc0, v5
	v_readlane_b32 s6, v252, 20
	v_readlane_b32 s8, v252, 51
	v_and_b32_e32 v4, -16, v4
	v_sub_u32_e32 v3, v3, v5
	v_readlane_b32 s7, v252, 21
	v_readlane_b32 s9, v252, 52
	v_add_u32_e32 v4, v11, v4
	v_ashrrev_i16_sdwa v3, v211, sext(v3) dst_sel:DWORD dst_unused:UNUSED_PAD src0_sel:DWORD src1_sel:BYTE_0
	s_cselect_b32 s58, s7, s9
	v_lshlrev_b32_e32 v6, 5, v10
	v_bfe_i32 v12, v3, 0, 16
	v_lshlrev_b32_e32 v3, 1, v4
	v_lshrrev_b32_e32 v5, 2, v4
	v_and_b32_e32 v7, 3, v11
	s_mov_b32 s7, 0xfffe0
	v_and_b32_e32 v6, 32, v6
	v_and_b32_e32 v3, 24, v3
	v_and_b32_e32 v5, 4, v5
	v_and_or_b32 v7, v4, s7, v7
	v_or3_b32 v3, v7, v5, v3
	v_add_lshl_u32 v5, v6, v12, 1
	v_add_u32_e32 v2, 0x2000, v2
	s_waitcnt vmcnt(0)
	v_lshl_add_u32 v156, v3, 12, v5
	v_ashrrev_i32_e32 v3, 31, v2
	v_lshrrev_b32_e32 v3, 22, v3
	v_add_u32_e32 v3, v2, v3
	v_ashrrev_i32_e32 v13, 10, v3
	v_mul_i32_i24_e32 v3, 0x400, v13
	v_sub_u32_e32 v2, v2, v3
	v_lshrrev_b32_e32 v3, 4, v2
	v_bitop3_b32 v2, v3, v2, 32 bitop3:0x6c
	v_lshl_add_u32 v110, v4, 12, v5
	v_ashrrev_i32_e32 v4, 31, v2
	v_lshrrev_b32_e32 v4, 26, v4
	s_cselect_b32 s59, s6, s8
	s_lshl_b32 s6, s16, 12
	v_lshlrev_b32_e32 v3, 3, v13
	v_add_u32_e32 v4, v2, v4
	s_add_u32 s54, s59, s6
	v_and_b32_e32 v3, -16, v3
	v_ashrrev_i32_e32 v14, 6, v4
	s_addc_u32 s37, s58, 0
	s_ashr_i32 s6, s40, 6
	v_add_u32_e32 v3, v14, v3
	v_and_b32_e32 v6, 3, v14
	s_ashr_i32 s97, s96, 31
	s_ashr_i32 s45, s44, 31
	v_and_or_b32 v6, v3, s7, v6
	s_ashr_i32 s7, s40, 8
	s_lshl_b32 s57, s6, 10
	s_lshl_b64 s[16:17], s[96:97], 20
	s_lshl_b64 s[8:9], s[44:45], 20
	v_and_b32_e32 v4, 0xc0, v4
	s_cmp_eq_u32 s64, 0
	v_sub_u32_e32 v2, v2, v4
	s_cselect_b32 s35, s59, s80
	v_ashrrev_i16_sdwa v2, v211, sext(v2) dst_sel:DWORD dst_unused:UNUSED_PAD src0_sel:DWORD src1_sel:BYTE_0
	s_cselect_b32 s34, s58, s81
	s_cselect_b32 s38, s81, s37
	s_cselect_b32 s39, s80, s54
	s_add_u32 s8, s35, s8
	v_lshlrev_b32_e32 v5, 5, v13
	v_bfe_i32 v15, v2, 0, 16
	v_lshlrev_b32_e32 v2, 1, v3
	v_lshrrev_b32_e32 v4, 2, v3
	s_addc_u32 s9, s34, s9
	s_add_i32 s97, s57, 0
	v_and_b32_e32 v5, 32, v5
	v_and_b32_e32 v2, 24, v2
	v_and_b32_e32 v4, 4, v4
	s_add_i32 m0, s97, 0x10000
	v_or3_b32 v2, v6, v4, v2
	v_add_lshl_u32 v4, v5, v15, 1
	global_load_lds_dwordx4 v156, s[8:9]
	s_add_i32 m0, s97, 0x12000
	v_lshl_add_u32 v160, v2, 12, v4
	s_add_u32 s34, s8, 0x80000
	global_load_lds_dwordx4 v160, s[8:9]
	s_addc_u32 s35, s9, 0
	s_add_i32 m0, s97, 0x14000
	v_lshl_add_u32 v158, v3, 12, v4
	global_load_lds_dwordx4 v156, s[34:35]
	s_add_i32 m0, s97, 0x16000
	s_add_u32 s42, s39, s16
	global_load_lds_dwordx4 v160, s[34:35]
	s_addc_u32 s43, s38, s17
	s_add_i32 s35, s97, 0x2000
	s_mov_b32 m0, s97
	s_add_u32 s16, s42, 0x80000
	global_load_lds_dwordx4 v110, s[42:43]
	s_mov_b32 m0, s35
	s_addc_u32 s17, s43, 0
	s_add_i32 s55, s97, 0x4000
	global_load_lds_dwordx4 v158, s[42:43]
	s_mov_b32 m0, s55
	s_add_i32 s34, s97, 0x6000
	global_load_lds_dwordx4 v110, s[16:17]
	s_mov_b32 m0, s34
	v_mov_b32_e32 v157, v0
	global_load_lds_dwordx4 v158, s[16:17]
	v_mov_b32_e32 v161, v0
	v_mov_b32_e32 v111, v0
	v_mov_b32_e32 v159, v0
	s_cmp_eq_u32 s7, 1
	v_readlane_b32 s41, v252, 16
	v_lshl_add_u64 v[8:9], s[8:9], 0, v[156:157]
	v_lshl_add_u64 v[6:7], s[8:9], 0, v[160:161]
	v_lshl_add_u64 v[2:3], s[42:43], 0, v[110:111]
	s_cselect_b64 s[74:75], -1, 0
	s_cmp_lg_u32 s7, 1
	v_lshl_add_u64 v[4:5], s[42:43], 0, v[158:159]
	s_cbranch_scc1 .LBB0_78
	s_barrier
	s_setprio 1

.LBB0_91:
	s_add_u32 s8, s42, 0xfff80080
	s_addc_u32 s9, s43, -1
	s_add_i32 s70, 0, 0x10000
	s_cmp_eq_u32 s69, 28
	s_cselect_b32 vcc_hi, s7, s9
	s_cselect_b32 vcc_lo, s45, s8
	v_add_u32_e32 v1, s70, v169
	s_cselect_b32 s9, s65, s68
	s_cselect_b32 s8, s66, s67
	s_add_i32 s72, 0, 0x14000
	ds_read_b128 v[136:139], v1
	ds_read_b128 v[140:143], v1 offset:1024
	ds_read_b128 v[144:147], v1 offset:2048
	ds_read_b128 v[148:151], v1 offset:3072
	v_add_u32_e32 v1, s72, v169
	ds_read_b128 v[152:155], v1
	ds_read_b128 v[186:189], v1 offset:1024
	ds_read_b128 v[190:193], v1 offset:2048
	ds_read_b128 v[194:197], v1 offset:3072
	v_lshl_add_u64 v[170:171], s[42:43], 0, v[162:163]
	s_add_i32 m0, s97, 0xc000
	ds_read_b128 v[198:201], v214
	ds_read_b128 v[216:219], v214 offset:1024
	ds_read_b128 v[220:223], v214 offset:2048
	ds_read_b128 v[224:227], v214 offset:3072
	ds_read_b128 v[228:231], v214 offset:4096
	ds_read_b128 v[232:235], v214 offset:5120
	ds_read_b128 v[236:239], v214 offset:6144
	ds_read_b128 v[240:243], v214 offset:7168
	global_load_lds_dwordx4 v[170:171], off
	v_lshl_add_u64 v[170:171], s[42:43], 0, v[184:185]
	s_add_i32 m0, s97, 0xe000
	s_nop 0
	global_load_lds_dwordx4 v[170:171], off
	s_waitcnt vmcnt(8)
	s_waitcnt lgkmcnt(0)
	s_barrier
	v_mfma_f32_16x16x32_bf16 v[132:135], v[136:139], v[198:201], v[132:135]
	v_mfma_f32_16x16x32_bf16 v[128:131], v[144:147], v[198:201], v[128:131]
	v_mfma_f32_16x16x32_bf16 v[116:119], v[136:139], v[220:223], v[116:119]
	v_mfma_f32_16x16x32_bf16 v[106:109], v[144:147], v[220:223], v[106:109]
	v_mfma_f32_16x16x32_bf16 v[94:97], v[136:139], v[228:231], v[94:97]
	v_mfma_f32_16x16x32_bf16 v[90:93], v[144:147], v[228:231], v[90:93]
	v_mfma_f32_16x16x32_bf16 v[78:81], v[136:139], v[236:239], v[78:81]
	v_mfma_f32_16x16x32_bf16 v[74:77], v[144:147], v[236:239], v[74:77]
	v_mfma_f32_16x16x32_bf16 v[132:135], v[140:143], v[216:219], v[132:135]
	v_mfma_f32_16x16x32_bf16 v[128:131], v[148:151], v[216:219], v[128:131]
	v_mfma_f32_16x16x32_bf16 v[116:119], v[140:143], v[224:227], v[116:119]
	v_mfma_f32_16x16x32_bf16 v[106:109], v[148:151], v[224:227], v[106:109]
	v_mfma_f32_16x16x32_bf16 v[94:97], v[140:143], v[232:235], v[94:97]
	v_mfma_f32_16x16x32_bf16 v[90:93], v[148:151], v[232:235], v[90:93]
	v_mfma_f32_16x16x32_bf16 v[78:81], v[140:143], v[240:243], v[78:81]
	v_mfma_f32_16x16x32_bf16 v[74:77], v[148:151], v[240:243], v[74:77]
	v_mfma_f32_16x16x32_bf16 v[124:127], v[152:155], v[198:201], v[124:127]
	v_mfma_f32_16x16x32_bf16 v[120:123], v[190:193], v[198:201], v[120:123]
	v_mfma_f32_16x16x32_bf16 v[102:105], v[152:155], v[220:223], v[102:105]
	v_mfma_f32_16x16x32_bf16 v[98:101], v[190:193], v[220:223], v[98:101]
	v_mfma_f32_16x16x32_bf16 v[86:89], v[152:155], v[228:231], v[86:89]
	v_mfma_f32_16x16x32_bf16 v[82:85], v[190:193], v[228:231], v[82:85]
	v_mfma_f32_16x16x32_bf16 v[70:73], v[152:155], v[236:239], v[70:73]
	v_mfma_f32_16x16x32_bf16 v[66:69], v[190:193], v[236:239], v[66:69]
	v_mfma_f32_16x16x32_bf16 v[124:127], v[186:189], v[216:219], v[124:127]
	v_mfma_f32_16x16x32_bf16 v[120:123], v[194:197], v[216:219], v[120:123]
	v_mfma_f32_16x16x32_bf16 v[102:105], v[186:189], v[224:227], v[102:105]
	v_mfma_f32_16x16x32_bf16 v[98:101], v[194:197], v[224:227], v[98:101]
	v_mfma_f32_16x16x32_bf16 v[86:89], v[186:189], v[232:235], v[86:89]
	v_mfma_f32_16x16x32_bf16 v[82:85], v[194:197], v[232:235], v[82:85]
	v_mfma_f32_16x16x32_bf16 v[70:73], v[186:189], v[240:243], v[70:73]
	v_mfma_f32_16x16x32_bf16 v[66:69], v[194:197], v[240:243], v[66:69]
	s_barrier
	s_add_i32 s70, s70, s57
	v_lshl_add_u64 v[170:171], s[8:9], 0, v[156:157]
	s_mov_b32 m0, s70
	ds_read_b128 v[198:201], v214 offset:16384
	ds_read_b128 v[216:219], v214 offset:17408
	ds_read_b128 v[220:223], v214 offset:18432
	ds_read_b128 v[224:227], v214 offset:19456
	ds_read_b128 v[228:231], v214 offset:20480
	ds_read_b128 v[232:235], v214 offset:21504
	ds_read_b128 v[236:239], v214 offset:22528
	ds_read_b128 v[240:243], v214 offset:23552
	global_load_lds_dwordx4 v[170:171], off
	s_add_i32 m0, s70, 0x2000
	s_add_u32 s70, s8, 0x80000
	v_lshl_add_u64 v[172:173], s[8:9], 0, v[160:161]
	s_addc_u32 s71, s9, 0
	s_add_i32 s72, s72, s57
	global_load_lds_dwordx4 v[172:173], off
	v_lshl_add_u64 v[244:245], s[70:71], 0, v[156:157]
	s_mov_b32 m0, s72
	v_lshl_add_u64 v[246:247], vcc, 0, v[158:159]
	global_load_lds_dwordx4 v[244:245], off
	v_lshl_add_u64 v[244:245], s[70:71], 0, v[160:161]
	s_add_i32 m0, s72, 0x2000
	s_nop 0
	global_load_lds_dwordx4 v[244:245], off
	v_lshl_add_u64 v[244:245], vcc, 0, v[110:111]
	s_mov_b32 m0, s97
	s_nop 0
	global_load_lds_dwordx4 v[244:245], off
	s_mov_b32 m0, s35
	s_nop 0
	global_load_lds_dwordx4 v[246:247], off
	s_waitcnt vmcnt(8)
	s_waitcnt lgkmcnt(0)
	s_barrier
	v_mfma_f32_16x16x32_bf16 v[62:65], v[136:139], v[198:201], v[62:65]
	v_mfma_f32_16x16x32_bf16 v[58:61], v[144:147], v[198:201], v[58:61]
	v_mfma_f32_16x16x32_bf16 v[46:49], v[136:139], v[220:223], v[46:49]
	v_mfma_f32_16x16x32_bf16 v[42:45], v[144:147], v[220:223], v[42:45]
	v_mfma_f32_16x16x32_bf16 v[30:33], v[136:139], v[228:231], v[30:33]
	v_mfma_f32_16x16x32_bf16 v[26:29], v[144:147], v[228:231], v[26:29]
	v_mfma_f32_16x16x32_bf16 v[14:17], v[136:139], v[236:239], v[14:17]
	v_mfma_f32_16x16x32_bf16 v[10:13], v[144:147], v[236:239], v[10:13]
	v_mfma_f32_16x16x32_bf16 v[62:65], v[140:143], v[216:219], v[62:65]
	v_mfma_f32_16x16x32_bf16 v[58:61], v[148:151], v[216:219], v[58:61]
	v_mfma_f32_16x16x32_bf16 v[46:49], v[140:143], v[224:227], v[46:49]
	v_mfma_f32_16x16x32_bf16 v[42:45], v[148:151], v[224:227], v[42:45]
	v_mfma_f32_16x16x32_bf16 v[30:33], v[140:143], v[232:235], v[30:33]
	v_mfma_f32_16x16x32_bf16 v[26:29], v[148:151], v[232:235], v[26:29]
	v_mfma_f32_16x16x32_bf16 v[14:17], v[140:143], v[240:243], v[14:17]
	v_mfma_f32_16x16x32_bf16 v[10:13], v[148:151], v[240:243], v[10:13]
	v_mfma_f32_16x16x32_bf16 v[54:57], v[152:155], v[198:201], v[54:57]
	v_mfma_f32_16x16x32_bf16 v[50:53], v[190:193], v[198:201], v[50:53]
	v_mfma_f32_16x16x32_bf16 v[38:41], v[152:155], v[220:223], v[38:41]
	v_mfma_f32_16x16x32_bf16 v[34:37], v[190:193], v[220:223], v[34:37]
	v_mfma_f32_16x16x32_bf16 v[22:25], v[152:155], v[228:231], v[22:25]
	v_mfma_f32_16x16x32_bf16 v[18:21], v[190:193], v[228:231], v[18:21]
	v_mfma_f32_16x16x32_bf16 v[6:9], v[152:155], v[236:239], v[6:9]
	v_mfma_f32_16x16x32_bf16 v[2:5], v[190:193], v[236:239], v[2:5]
	v_mfma_f32_16x16x32_bf16 v[54:57], v[186:189], v[216:219], v[54:57]
	v_mfma_f32_16x16x32_bf16 v[50:53], v[194:197], v[216:219], v[50:53]
	v_mfma_f32_16x16x32_bf16 v[38:41], v[186:189], v[224:227], v[38:41]
	v_mfma_f32_16x16x32_bf16 v[34:37], v[194:197], v[224:227], v[34:37]
	v_mfma_f32_16x16x32_bf16 v[22:25], v[186:189], v[232:235], v[22:25]
	v_mfma_f32_16x16x32_bf16 v[18:21], v[194:197], v[232:235], v[18:21]
	v_mfma_f32_16x16x32_bf16 v[6:9], v[186:189], v[240:243], v[6:9]
	v_mfma_f32_16x16x32_bf16 v[2:5], v[194:197], v[240:243], v[2:5]
	s_barrier
	s_add_i32 s72, 0, 0x18000
	v_add_u32_e32 v1, s72, v169
	s_add_i32 s73, 0, 0x1c000
	ds_read_b128 v[136:139], v1
	ds_read_b128 v[140:143], v1 offset:1024
	ds_read_b128 v[144:147], v1 offset:2048
	ds_read_b128 v[148:151], v1 offset:3072
	v_add_u32_e32 v1, s73, v169
	ds_read_b128 v[152:155], v1
	ds_read_b128 v[186:189], v1 offset:1024
	ds_read_b128 v[190:193], v1 offset:2048
	ds_read_b128 v[194:197], v1 offset:3072
	s_add_u32 s70, vcc_lo, 0x80000
	s_addc_u32 s71, vcc_hi, 0
	s_mov_b32 m0, s55
	v_lshl_add_u64 v[248:249], s[70:71], 0, v[110:111]
	ds_read_b128 v[198:201], v214 offset:32768
	ds_read_b128 v[216:219], v214 offset:33792
	ds_read_b128 v[220:223], v214 offset:34816
	ds_read_b128 v[224:227], v214 offset:35840
	ds_read_b128 v[228:231], v214 offset:36864
	ds_read_b128 v[232:235], v214 offset:37888
	ds_read_b128 v[236:239], v214 offset:38912
	ds_read_b128 v[240:243], v214 offset:39936
	global_load_lds_dwordx4 v[248:249], off
	v_lshl_add_u64 v[248:249], s[70:71], 0, v[158:159]
	s_mov_b32 m0, s34
	s_nop 0
	global_load_lds_dwordx4 v[248:249], off
	s_waitcnt vmcnt(8)
	s_waitcnt lgkmcnt(0)
	s_barrier
	v_mfma_f32_16x16x32_bf16 v[132:135], v[136:139], v[198:201], v[132:135]
	v_mfma_f32_16x16x32_bf16 v[128:131], v[144:147], v[198:201], v[128:131]
	v_mfma_f32_16x16x32_bf16 v[116:119], v[136:139], v[220:223], v[116:119]
	v_mfma_f32_16x16x32_bf16 v[106:109], v[144:147], v[220:223], v[106:109]
	v_mfma_f32_16x16x32_bf16 v[94:97], v[136:139], v[228:231], v[94:97]
	v_mfma_f32_16x16x32_bf16 v[90:93], v[144:147], v[228:231], v[90:93]
	v_mfma_f32_16x16x32_bf16 v[78:81], v[136:139], v[236:239], v[78:81]
	v_mfma_f32_16x16x32_bf16 v[74:77], v[144:147], v[236:239], v[74:77]
	v_mfma_f32_16x16x32_bf16 v[132:135], v[140:143], v[216:219], v[132:135]
	v_mfma_f32_16x16x32_bf16 v[128:131], v[148:151], v[216:219], v[128:131]
	v_mfma_f32_16x16x32_bf16 v[116:119], v[140:143], v[224:227], v[116:119]
	v_mfma_f32_16x16x32_bf16 v[106:109], v[148:151], v[224:227], v[106:109]
	v_mfma_f32_16x16x32_bf16 v[94:97], v[140:143], v[232:235], v[94:97]
	v_mfma_f32_16x16x32_bf16 v[90:93], v[148:151], v[232:235], v[90:93]
	v_mfma_f32_16x16x32_bf16 v[78:81], v[140:143], v[240:243], v[78:81]
	v_mfma_f32_16x16x32_bf16 v[74:77], v[148:151], v[240:243], v[74:77]
	v_mfma_f32_16x16x32_bf16 v[124:127], v[152:155], v[198:201], v[124:127]
	v_mfma_f32_16x16x32_bf16 v[120:123], v[190:193], v[198:201], v[120:123]
	v_mfma_f32_16x16x32_bf16 v[102:105], v[152:155], v[220:223], v[102:105]
	v_mfma_f32_16x16x32_bf16 v[98:101], v[190:193], v[220:223], v[98:101]
	v_mfma_f32_16x16x32_bf16 v[86:89], v[152:155], v[228:231], v[86:89]
	v_mfma_f32_16x16x32_bf16 v[82:85], v[190:193], v[228:231], v[82:85]
	v_mfma_f32_16x16x32_bf16 v[70:73], v[152:155], v[236:239], v[70:73]
	v_mfma_f32_16x16x32_bf16 v[66:69], v[190:193], v[236:239], v[66:69]
	v_mfma_f32_16x16x32_bf16 v[124:127], v[186:189], v[216:219], v[124:127]
	v_mfma_f32_16x16x32_bf16 v[120:123], v[194:197], v[216:219], v[120:123]
	v_mfma_f32_16x16x32_bf16 v[102:105], v[186:189], v[224:227], v[102:105]
	v_mfma_f32_16x16x32_bf16 v[98:101], v[194:197], v[224:227], v[98:101]
	v_mfma_f32_16x16x32_bf16 v[86:89], v[186:189], v[232:235], v[86:89]
	v_mfma_f32_16x16x32_bf16 v[82:85], v[194:197], v[232:235], v[82:85]
	v_mfma_f32_16x16x32_bf16 v[70:73], v[186:189], v[240:243], v[70:73]
	v_mfma_f32_16x16x32_bf16 v[66:69], v[194:197], v[240:243], v[66:69]
	s_barrier
	s_add_i32 s70, s72, s57
	v_lshl_add_u64 v[170:171], v[170:171], 0, s[26:27]
	s_mov_b32 m0, s70
	ds_read_b128 v[198:201], v214 offset:49152
	ds_read_b128 v[216:219], v214 offset:50176
	ds_read_b128 v[220:223], v214 offset:51200
	ds_read_b128 v[224:227], v214 offset:52224
	ds_read_b128 v[228:231], v214 offset:53248
	ds_read_b128 v[232:235], v214 offset:54272
	ds_read_b128 v[236:239], v214 offset:55296
	ds_read_b128 v[240:243], v214 offset:56320
	global_load_lds_dwordx4 v[170:171], off
	s_add_i32 m0, s70, 0x2000
	s_add_u32 s8, s8, 0x80080
	v_lshl_add_u64 v[170:171], v[172:173], 0, s[26:27]
	s_addc_u32 s9, s9, 0
	s_add_i32 s70, s73, s57
	global_load_lds_dwordx4 v[170:171], off
	v_lshl_add_u64 v[170:171], s[8:9], 0, v[156:157]
	s_mov_b32 m0, s70
	s_nop 0
	global_load_lds_dwordx4 v[170:171], off
	v_lshl_add_u64 v[170:171], s[8:9], 0, v[160:161]
	s_add_i32 m0, s70, 0x2000
	s_nop 0
	global_load_lds_dwordx4 v[170:171], off
	v_lshl_add_u64 v[170:171], v[244:245], 0, s[26:27]
	s_mov_b32 m0, s60
	s_nop 0
	global_load_lds_dwordx4 v[170:171], off
	v_lshl_add_u64 v[170:171], v[246:247], 0, s[26:27]
	s_mov_b32 m0, s61
	s_nop 0
	global_load_lds_dwordx4 v[170:171], off
	s_waitcnt vmcnt(8)
	s_waitcnt lgkmcnt(0)
	s_barrier
	v_mfma_f32_16x16x32_bf16 v[62:65], v[136:139], v[198:201], v[62:65]
	v_mfma_f32_16x16x32_bf16 v[58:61], v[144:147], v[198:201], v[58:61]
	v_mfma_f32_16x16x32_bf16 v[46:49], v[136:139], v[220:223], v[46:49]
	v_mfma_f32_16x16x32_bf16 v[42:45], v[144:147], v[220:223], v[42:45]
	v_mfma_f32_16x16x32_bf16 v[30:33], v[136:139], v[228:231], v[30:33]
	v_mfma_f32_16x16x32_bf16 v[26:29], v[144:147], v[228:231], v[26:29]
	v_mfma_f32_16x16x32_bf16 v[14:17], v[136:139], v[236:239], v[14:17]
	v_mfma_f32_16x16x32_bf16 v[10:13], v[144:147], v[236:239], v[10:13]
	v_mfma_f32_16x16x32_bf16 v[62:65], v[140:143], v[216:219], v[62:65]
	v_mfma_f32_16x16x32_bf16 v[58:61], v[148:151], v[216:219], v[58:61]
	v_mfma_f32_16x16x32_bf16 v[46:49], v[140:143], v[224:227], v[46:49]
	v_mfma_f32_16x16x32_bf16 v[42:45], v[148:151], v[224:227], v[42:45]
	v_mfma_f32_16x16x32_bf16 v[30:33], v[140:143], v[232:235], v[30:33]
	v_mfma_f32_16x16x32_bf16 v[26:29], v[148:151], v[232:235], v[26:29]
	v_mfma_f32_16x16x32_bf16 v[14:17], v[140:143], v[240:243], v[14:17]
	v_mfma_f32_16x16x32_bf16 v[10:13], v[148:151], v[240:243], v[10:13]
	v_mfma_f32_16x16x32_bf16 v[54:57], v[152:155], v[198:201], v[54:57]
	v_mfma_f32_16x16x32_bf16 v[50:53], v[190:193], v[198:201], v[50:53]
	v_mfma_f32_16x16x32_bf16 v[38:41], v[152:155], v[220:223], v[38:41]
	v_mfma_f32_16x16x32_bf16 v[34:37], v[190:193], v[220:223], v[34:37]
	v_mfma_f32_16x16x32_bf16 v[22:25], v[152:155], v[228:231], v[22:25]
	v_mfma_f32_16x16x32_bf16 v[18:21], v[190:193], v[228:231], v[18:21]
	v_mfma_f32_16x16x32_bf16 v[6:9], v[152:155], v[236:239], v[6:9]
	v_mfma_f32_16x16x32_bf16 v[2:5], v[190:193], v[236:239], v[2:5]
	v_mfma_f32_16x16x32_bf16 v[54:57], v[186:189], v[216:219], v[54:57]
	v_mfma_f32_16x16x32_bf16 v[50:53], v[194:197], v[216:219], v[50:53]
	v_mfma_f32_16x16x32_bf16 v[38:41], v[186:189], v[224:227], v[38:41]
	v_mfma_f32_16x16x32_bf16 v[34:37], v[194:197], v[224:227], v[34:37]
	v_mfma_f32_16x16x32_bf16 v[22:25], v[186:189], v[232:235], v[22:25]
	v_mfma_f32_16x16x32_bf16 v[18:21], v[194:197], v[232:235], v[18:21]
	v_mfma_f32_16x16x32_bf16 v[6:9], v[186:189], v[240:243], v[6:9]
	v_mfma_f32_16x16x32_bf16 v[2:5], v[194:197], v[240:243], v[2:5]
	s_barrier
	s_add_i32 s69, s69, 2
	s_add_u32 s42, s42, 0x100
	s_addc_u32 s43, s43, 0
	s_add_u32 s67, s67, 0x100
	s_addc_u32 s68, s68, 0
	s_cmp_gt_u32 s69, 29
	s_cbranch_scc0 .LBB0_91
	s_and_b64 vcc, exec, s[16:17]
	s_cbranch_vccz .LBB0_94
	s_barrier

.LBB0_191:
	s_setprio 0
	s_waitcnt vmcnt(0)
	v_readlane_b32 s86, v254, 61
	v_readlane_b32 s84, v255, 0
	v_readlane_b32 s58, v255, 2
	v_readlane_b32 s60, v255, 4
	v_readlane_b32 s62, v255, 6
	v_readlane_b32 s54, v255, 10
	v_readlane_b32 s92, v255, 14
	v_readlane_b32 s72, v254, 59
	v_readlane_b32 s73, v254, 60
	v_readlane_b32 s87, v254, 62
	v_readlane_b32 s74, v254, 63
	v_readlane_b32 s85, v255, 1
	v_readlane_b32 s59, v255, 3
	v_readlane_b32 s61, v255, 5
	v_readlane_b32 s63, v255, 7
	v_readlane_b32 s55, v255, 11
	s_movk_i32 s94, 0x1fff
	v_readlane_b32 s93, v255, 15
	s_barrier

.LBB0_539:
	v_readlane_b32 s42, v254, 55
	v_readlane_b32 s43, v254, 56
	s_and_b64 vcc, exec, s[38:39]
	s_cbranch_vccnz .LBB0_580
	v_ashrrev_i32_e32 v3, 31, v1
	v_lshrrev_b32_e32 v3, 26, v3
	v_add_u32_e32 v3, v1, v3
	v_ashrrev_i32_e32 v10, 6, v3
	v_bfe_i32 v3, v1, 27, 1
	v_lshlrev_b32_e32 v2, 4, v1
	v_lshrrev_b32_e32 v3, 22, v3
	v_add_u32_e32 v3, v2, v3
	v_and_b32_e32 v3, 0xfffffc00, v3
	v_sub_u32_e32 v3, v2, v3
	v_lshrrev_b32_e32 v4, 4, v3
	v_bitop3_b32 v3, v4, v3, 32 bitop3:0x6c
	v_ashrrev_i32_e32 v5, 31, v3
	v_lshrrev_b32_e32 v5, 26, v5
	v_add_u32_e32 v5, v3, v5
	v_lshlrev_b32_e32 v4, 3, v10
	v_ashrrev_i32_e32 v11, 6, v5
	v_and_b32_e32 v5, 0xc0, v5
	v_and_b32_e32 v4, -16, v4
	v_sub_u32_e32 v3, v3, v5
	v_add_u32_e32 v4, v11, v4
	v_ashrrev_i16_sdwa v3, v211, sext(v3) dst_sel:DWORD dst_unused:UNUSED_PAD src0_sel:DWORD src1_sel:BYTE_0
	v_lshlrev_b32_e32 v6, 5, v10
	v_bfe_i32 v12, v3, 0, 16
	v_lshlrev_b32_e32 v3, 1, v4
	v_lshrrev_b32_e32 v5, 2, v4
	v_and_b32_e32 v7, 3, v11
	s_mov_b32 s7, 0xfffe0
	v_and_b32_e32 v6, 32, v6
	v_and_b32_e32 v3, 24, v3
	v_and_b32_e32 v5, 4, v5
	v_and_or_b32 v7, v4, s7, v7
	v_or3_b32 v3, v7, v5, v3
	v_add_lshl_u32 v5, v6, v12, 1
	v_add_u32_e32 v2, 0x2000, v2
	s_waitcnt vmcnt(0)
	v_lshl_add_u32 v136, v3, 12, v5
	v_ashrrev_i32_e32 v3, 31, v2
	v_lshrrev_b32_e32 v3, 22, v3
	v_add_u32_e32 v3, v2, v3
	v_ashrrev_i32_e32 v13, 10, v3
	v_mul_i32_i24_e32 v3, 0x400, v13
	s_ashr_i32 s38, s44, 6
	v_sub_u32_e32 v2, v2, v3
	v_readlane_b32 s8, v254, 57
	v_lshrrev_b32_e32 v3, 4, v2
	s_ashr_i32 s39, s44, 8
	s_lshl_b32 s54, s38, 10
	v_readlane_b32 s9, v254, 58
	v_bitop3_b32 v2, v3, v2, 32 bitop3:0x6c
	s_and_b64 s[8:9], s[8:9], exec
	v_lshl_add_u32 v110, v4, 12, v5
	v_ashrrev_i32_e32 v4, 31, v2
	v_readlane_b32 s8, v252, 45
	v_readlane_b32 s42, v252, 53
	v_lshrrev_b32_e32 v4, 26, v4
	v_readlane_b32 s9, v252, 46
	v_readlane_b32 s43, v252, 54
	v_lshlrev_b32_e32 v3, 3, v13
	v_add_u32_e32 v4, v2, v4
	s_cselect_b32 s55, s9, s43
	s_cselect_b32 s56, s8, s42
	s_ashr_i32 s17, s16, 31
	v_and_b32_e32 v3, -16, v3
	v_ashrrev_i32_e32 v14, 6, v4
	s_lshl_b64 s[8:9], s[16:17], 20
	v_readlane_b32 s42, v252, 59
	v_add_u32_e32 v3, v14, v3
	v_and_b32_e32 v6, 3, v14
	v_readlane_b32 s43, v252, 60
	s_add_u32 s45, s42, s8
	v_and_or_b32 v6, v3, s7, v6
	s_addc_u32 s46, s43, s9
	s_ashr_i32 s7, s6, 31
	s_lshl_b64 s[8:9], s[6:7], 20
	v_and_b32_e32 v4, 0xc0, v4
	s_add_u32 s7, s56, s8
	v_sub_u32_e32 v2, v2, v4
	s_addc_u32 s9, s55, s9
	v_ashrrev_i16_sdwa v2, v211, sext(v2) dst_sel:DWORD dst_unused:UNUSED_PAD src0_sel:DWORD src1_sel:BYTE_0
	s_add_u32 s8, s7, s40
	v_lshlrev_b32_e32 v5, 5, v13
	v_bfe_i32 v15, v2, 0, 16
	v_lshlrev_b32_e32 v2, 1, v3
	v_lshrrev_b32_e32 v4, 2, v3
	s_addc_u32 s9, s9, s41
	s_add_i32 s17, s54, 0
	v_and_b32_e32 v5, 32, v5
	v_and_b32_e32 v2, 24, v2
	v_and_b32_e32 v4, 4, v4
	s_add_i32 m0, s17, 0x10000
	v_or3_b32 v2, v6, v4, v2
	v_add_lshl_u32 v4, v5, v15, 1
	global_load_lds_dwordx4 v136, s[8:9]
	s_add_i32 m0, s17, 0x12000
	v_lshl_add_u32 v140, v2, 12, v4
	s_add_u32 s42, s8, 0x80000
	global_load_lds_dwordx4 v140, s[8:9]
	s_addc_u32 s43, s9, 0
	s_add_i32 m0, s17, 0x14000
	v_lshl_add_u32 v138, v3, 12, v4
	global_load_lds_dwordx4 v136, s[42:43]
	s_add_i32 m0, s17, 0x16000
	s_add_u32 s92, s45, s40
	s_addc_u32 s93, s46, s41
	s_add_i32 s58, s17, 0x2000
	global_load_lds_dwordx4 v140, s[42:43]
	s_mov_b32 m0, s17
	s_add_u32 s40, s92, 0x80000
	global_load_lds_dwordx4 v110, s[92:93]
	s_mov_b32 m0, s58
	s_addc_u32 s41, s93, 0
	s_add_i32 s59, s17, 0x4000
	global_load_lds_dwordx4 v138, s[92:93]
	s_mov_b32 m0, s59
	s_add_i32 s60, s17, 0x6000
	global_load_lds_dwordx4 v110, s[40:41]
	s_mov_b32 m0, s60
	v_mov_b32_e32 v137, v0
	global_load_lds_dwordx4 v138, s[40:41]
	v_mov_b32_e32 v141, v0
	v_mov_b32_e32 v111, v0
	v_mov_b32_e32 v139, v0
	s_cmp_eq_u32 s39, 1
	v_lshl_add_u64 v[8:9], s[8:9], 0, v[136:137]
	v_lshl_add_u64 v[6:7], s[8:9], 0, v[140:141]
	v_lshl_add_u64 v[2:3], s[92:93], 0, v[110:111]
	s_cselect_b64 s[42:43], -1, 0
	s_cmp_lg_u32 s39, 1
	v_lshl_add_u64 v[4:5], s[92:93], 0, v[138:139]
	s_cbranch_scc1 .LBB0_542
	s_barrier
	s_setprio 1

.LBB0_553:
	s_add_i32 s72, s8, 2
	s_add_u32 s9, s92, 0xfff80080
	s_addc_u32 s73, s93, -1
	s_add_i32 s74, 0, 0x10000
	s_cmp_eq_u32 s69, s8
	s_cselect_b32 s95, s7, s73
	s_cselect_b32 s94, s49, s9
	v_add_u32_e32 v154, s74, v1
	s_cselect_b32 s9, s47, s71
	s_cselect_b32 s8, s68, s70
	s_add_i32 s73, 0, 0x14000
	s_waitcnt lgkmcnt(0)
	ds_read_b128 v[150:153], v154
	ds_read_b128 v[158:161], v154 offset:1024
	ds_read_b128 v[184:187], v154 offset:2048
	ds_read_b128 v[188:191], v154 offset:3072
	v_add_u32_e32 v154, s73, v1
	ds_read_b128 v[192:195], v154
	ds_read_b128 v[196:199], v154 offset:1024
	ds_read_b128 v[214:217], v154 offset:2048
	ds_read_b128 v[218:221], v154 offset:3072
	v_lshl_add_u64 v[154:155], s[92:93], 0, v[146:147]
	s_add_i32 m0, s17, 0xc000
	ds_read_b128 v[222:225], v156
	ds_read_b128 v[226:229], v156 offset:1024
	ds_read_b128 v[230:233], v156 offset:2048
	ds_read_b128 v[234:237], v156 offset:3072
	ds_read_b128 v[238:241], v156 offset:4096
	ds_read_b128 v[242:245], v156 offset:5120
	ds_read_b128 v[246:249], v156 offset:6144
	ds_read_b128 v[170:173], v156 offset:7168
	global_load_lds_dwordx4 v[154:155], off
	v_lshl_add_u64 v[154:155], s[92:93], 0, v[148:149]
	s_add_i32 m0, s17, 0xe000
	s_nop 0
	global_load_lds_dwordx4 v[154:155], off
	s_waitcnt vmcnt(8)
	s_waitcnt lgkmcnt(0)
	s_barrier
	v_mfma_f32_16x16x32_bf16 v[132:135], v[150:153], v[222:225], v[132:135]
	v_mfma_f32_16x16x32_bf16 v[128:131], v[184:187], v[222:225], v[128:131]
	v_mfma_f32_16x16x32_bf16 v[124:127], v[150:153], v[230:233], v[124:127]
	v_mfma_f32_16x16x32_bf16 v[120:123], v[184:187], v[230:233], v[120:123]
	v_mfma_f32_16x16x32_bf16 v[106:109], v[150:153], v[238:241], v[106:109]
	v_mfma_f32_16x16x32_bf16 v[98:101], v[184:187], v[238:241], v[98:101]
	v_mfma_f32_16x16x32_bf16 v[90:93], v[150:153], v[246:249], v[90:93]
	v_mfma_f32_16x16x32_bf16 v[82:85], v[184:187], v[246:249], v[82:85]
	v_mfma_f32_16x16x32_bf16 v[132:135], v[158:161], v[226:229], v[132:135]
	v_mfma_f32_16x16x32_bf16 v[128:131], v[188:191], v[226:229], v[128:131]
	v_mfma_f32_16x16x32_bf16 v[124:127], v[158:161], v[234:237], v[124:127]
	v_mfma_f32_16x16x32_bf16 v[120:123], v[188:191], v[234:237], v[120:123]
	v_mfma_f32_16x16x32_bf16 v[106:109], v[158:161], v[242:245], v[106:109]
	v_mfma_f32_16x16x32_bf16 v[98:101], v[188:191], v[242:245], v[98:101]
	v_mfma_f32_16x16x32_bf16 v[90:93], v[158:161], v[170:173], v[90:93]
	v_mfma_f32_16x16x32_bf16 v[82:85], v[188:191], v[170:173], v[82:85]
	v_mfma_f32_16x16x32_bf16 v[116:119], v[192:195], v[222:225], v[116:119]
	v_mfma_f32_16x16x32_bf16 v[102:105], v[214:217], v[222:225], v[102:105]
	v_mfma_f32_16x16x32_bf16 v[94:97], v[192:195], v[230:233], v[94:97]
	v_mfma_f32_16x16x32_bf16 v[86:89], v[214:217], v[230:233], v[86:89]
	v_mfma_f32_16x16x32_bf16 v[78:81], v[192:195], v[238:241], v[78:81]
	v_mfma_f32_16x16x32_bf16 v[74:77], v[214:217], v[238:241], v[74:77]
	v_mfma_f32_16x16x32_bf16 v[70:73], v[192:195], v[246:249], v[70:73]
	v_mfma_f32_16x16x32_bf16 v[66:69], v[214:217], v[246:249], v[66:69]
	v_mfma_f32_16x16x32_bf16 v[116:119], v[196:199], v[226:229], v[116:119]
	v_mfma_f32_16x16x32_bf16 v[102:105], v[218:221], v[226:229], v[102:105]
	v_mfma_f32_16x16x32_bf16 v[94:97], v[196:199], v[234:237], v[94:97]
	v_mfma_f32_16x16x32_bf16 v[86:89], v[218:221], v[234:237], v[86:89]
	v_mfma_f32_16x16x32_bf16 v[78:81], v[196:199], v[242:245], v[78:81]
	v_mfma_f32_16x16x32_bf16 v[74:77], v[218:221], v[242:245], v[74:77]
	v_mfma_f32_16x16x32_bf16 v[70:73], v[196:199], v[170:173], v[70:73]
	v_mfma_f32_16x16x32_bf16 v[66:69], v[218:221], v[170:173], v[66:69]
	s_barrier
	s_add_i32 s74, s74, s54
	v_lshl_add_u64 v[154:155], s[8:9], 0, v[136:137]
	s_mov_b32 m0, s74
	ds_read_b128 v[170:173], v156 offset:16384
	ds_read_b128 v[222:225], v156 offset:17408
	ds_read_b128 v[226:229], v156 offset:18432
	ds_read_b128 v[230:233], v156 offset:19456
	ds_read_b128 v[234:237], v156 offset:20480
	ds_read_b128 v[238:241], v156 offset:21504
	ds_read_b128 v[242:245], v156 offset:22528
	ds_read_b128 v[246:249], v156 offset:23552
	global_load_lds_dwordx4 v[154:155], off
	s_add_i32 m0, s74, 0x2000
	s_add_u32 s74, s8, 0x80000
	v_lshl_add_u64 v[162:163], s[8:9], 0, v[140:141]
	s_addc_u32 s75, s9, 0
	s_add_i32 s73, s73, s54
	global_load_lds_dwordx4 v[162:163], off
	v_lshl_add_u64 v[200:201], s[74:75], 0, v[136:137]
	s_mov_b32 m0, s73
	v_lshl_add_u64 v[250:251], s[94:95], 0, v[138:139]
	global_load_lds_dwordx4 v[200:201], off
	v_lshl_add_u64 v[200:201], s[74:75], 0, v[140:141]
	s_add_i32 m0, s73, 0x2000
	s_nop 0
	global_load_lds_dwordx4 v[200:201], off
	v_lshl_add_u64 v[200:201], s[94:95], 0, v[110:111]
	s_mov_b32 m0, s17
	s_nop 0
	global_load_lds_dwordx4 v[200:201], off
	s_mov_b32 m0, s58
	s_nop 0
	global_load_lds_dwordx4 v[250:251], off
	s_waitcnt vmcnt(8)
	s_waitcnt lgkmcnt(0)
	s_barrier
	v_mfma_f32_16x16x32_bf16 v[62:65], v[150:153], v[170:173], v[62:65]
	v_mfma_f32_16x16x32_bf16 v[58:61], v[184:187], v[170:173], v[58:61]
	v_mfma_f32_16x16x32_bf16 v[54:57], v[150:153], v[226:229], v[54:57]
	v_mfma_f32_16x16x32_bf16 v[50:53], v[184:187], v[226:229], v[50:53]
	v_mfma_f32_16x16x32_bf16 v[42:45], v[150:153], v[234:237], v[42:45]
	v_mfma_f32_16x16x32_bf16 v[34:37], v[184:187], v[234:237], v[34:37]
	v_mfma_f32_16x16x32_bf16 v[26:29], v[150:153], v[242:245], v[26:29]
	v_mfma_f32_16x16x32_bf16 v[18:21], v[184:187], v[242:245], v[18:21]
	v_mfma_f32_16x16x32_bf16 v[62:65], v[158:161], v[222:225], v[62:65]
	v_mfma_f32_16x16x32_bf16 v[58:61], v[188:191], v[222:225], v[58:61]
	v_mfma_f32_16x16x32_bf16 v[54:57], v[158:161], v[230:233], v[54:57]
	v_mfma_f32_16x16x32_bf16 v[50:53], v[188:191], v[230:233], v[50:53]
	v_mfma_f32_16x16x32_bf16 v[42:45], v[158:161], v[238:241], v[42:45]
	v_mfma_f32_16x16x32_bf16 v[34:37], v[188:191], v[238:241], v[34:37]
	v_mfma_f32_16x16x32_bf16 v[26:29], v[158:161], v[246:249], v[26:29]
	v_mfma_f32_16x16x32_bf16 v[18:21], v[188:191], v[246:249], v[18:21]
	v_mfma_f32_16x16x32_bf16 v[46:49], v[192:195], v[170:173], v[46:49]
	v_mfma_f32_16x16x32_bf16 v[38:41], v[214:217], v[170:173], v[38:41]
	v_mfma_f32_16x16x32_bf16 v[30:33], v[192:195], v[226:229], v[30:33]
	v_mfma_f32_16x16x32_bf16 v[22:25], v[214:217], v[226:229], v[22:25]
	v_mfma_f32_16x16x32_bf16 v[14:17], v[192:195], v[234:237], v[14:17]
	v_mfma_f32_16x16x32_bf16 v[10:13], v[214:217], v[234:237], v[10:13]
	v_mfma_f32_16x16x32_bf16 v[6:9], v[192:195], v[242:245], v[6:9]
	v_mfma_f32_16x16x32_bf16 v[2:5], v[214:217], v[242:245], v[2:5]
	v_mfma_f32_16x16x32_bf16 v[46:49], v[196:199], v[222:225], v[46:49]
	v_mfma_f32_16x16x32_bf16 v[38:41], v[218:221], v[222:225], v[38:41]
	v_mfma_f32_16x16x32_bf16 v[30:33], v[196:199], v[230:233], v[30:33]
	v_mfma_f32_16x16x32_bf16 v[22:25], v[218:221], v[230:233], v[22:25]
	v_mfma_f32_16x16x32_bf16 v[14:17], v[196:199], v[238:241], v[14:17]
	v_mfma_f32_16x16x32_bf16 v[10:13], v[218:221], v[238:241], v[10:13]
	v_mfma_f32_16x16x32_bf16 v[6:9], v[196:199], v[246:249], v[6:9]
	v_mfma_f32_16x16x32_bf16 v[2:5], v[218:221], v[246:249], v[2:5]
	s_barrier
	s_add_i32 s73, 0, 0x18000
	v_add_u32_e32 v157, s73, v1
	s_add_i32 s88, 0, 0x1c000
	ds_read_b128 v[150:153], v157
	ds_read_b128 v[158:161], v157 offset:1024
	ds_read_b128 v[170:173], v157 offset:2048
	ds_read_b128 v[184:187], v157 offset:3072
	v_add_u32_e32 v157, s88, v1
	ds_read_b128 v[188:191], v157
	ds_read_b128 v[192:195], v157 offset:1024
	ds_read_b128 v[196:199], v157 offset:2048
	ds_read_b128 v[214:217], v157 offset:3072
	s_add_u32 s74, s94, 0x80000
	s_addc_u32 s75, s95, 0
	s_mov_b32 m0, s59
	v_lshl_add_u64 v[206:207], s[74:75], 0, v[110:111]
	ds_read_b128 v[218:221], v156 offset:32768
	ds_read_b128 v[222:225], v156 offset:33792
	ds_read_b128 v[226:229], v156 offset:34816
	ds_read_b128 v[230:233], v156 offset:35840
	ds_read_b128 v[234:237], v156 offset:36864
	ds_read_b128 v[238:241], v156 offset:37888
	ds_read_b128 v[242:245], v156 offset:38912
	ds_read_b128 v[246:249], v156 offset:39936
	global_load_lds_dwordx4 v[206:207], off
	v_lshl_add_u64 v[206:207], s[74:75], 0, v[138:139]
	s_mov_b32 m0, s60
	s_nop 0
	global_load_lds_dwordx4 v[206:207], off
	s_waitcnt vmcnt(8)
	s_waitcnt lgkmcnt(0)
	s_barrier
	v_mfma_f32_16x16x32_bf16 v[132:135], v[150:153], v[218:221], v[132:135]
	v_mfma_f32_16x16x32_bf16 v[128:131], v[170:173], v[218:221], v[128:131]
	v_mfma_f32_16x16x32_bf16 v[124:127], v[150:153], v[226:229], v[124:127]
	v_mfma_f32_16x16x32_bf16 v[120:123], v[170:173], v[226:229], v[120:123]
	v_mfma_f32_16x16x32_bf16 v[106:109], v[150:153], v[234:237], v[106:109]
	v_mfma_f32_16x16x32_bf16 v[98:101], v[170:173], v[234:237], v[98:101]
	v_mfma_f32_16x16x32_bf16 v[90:93], v[150:153], v[242:245], v[90:93]
	v_mfma_f32_16x16x32_bf16 v[82:85], v[170:173], v[242:245], v[82:85]
	v_mfma_f32_16x16x32_bf16 v[132:135], v[158:161], v[222:225], v[132:135]
	v_mfma_f32_16x16x32_bf16 v[128:131], v[184:187], v[222:225], v[128:131]
	v_mfma_f32_16x16x32_bf16 v[124:127], v[158:161], v[230:233], v[124:127]
	v_mfma_f32_16x16x32_bf16 v[120:123], v[184:187], v[230:233], v[120:123]
	v_mfma_f32_16x16x32_bf16 v[106:109], v[158:161], v[238:241], v[106:109]
	v_mfma_f32_16x16x32_bf16 v[98:101], v[184:187], v[238:241], v[98:101]
	v_mfma_f32_16x16x32_bf16 v[90:93], v[158:161], v[246:249], v[90:93]
	v_mfma_f32_16x16x32_bf16 v[82:85], v[184:187], v[246:249], v[82:85]
	v_mfma_f32_16x16x32_bf16 v[116:119], v[188:191], v[218:221], v[116:119]
	v_mfma_f32_16x16x32_bf16 v[102:105], v[196:199], v[218:221], v[102:105]
	v_mfma_f32_16x16x32_bf16 v[94:97], v[188:191], v[226:229], v[94:97]
	v_mfma_f32_16x16x32_bf16 v[86:89], v[196:199], v[226:229], v[86:89]
	v_mfma_f32_16x16x32_bf16 v[78:81], v[188:191], v[234:237], v[78:81]
	v_mfma_f32_16x16x32_bf16 v[74:77], v[196:199], v[234:237], v[74:77]
	v_mfma_f32_16x16x32_bf16 v[70:73], v[188:191], v[242:245], v[70:73]
	v_mfma_f32_16x16x32_bf16 v[66:69], v[196:199], v[242:245], v[66:69]
	v_mfma_f32_16x16x32_bf16 v[116:119], v[192:195], v[222:225], v[116:119]
	v_mfma_f32_16x16x32_bf16 v[102:105], v[214:217], v[222:225], v[102:105]
	v_mfma_f32_16x16x32_bf16 v[94:97], v[192:195], v[230:233], v[94:97]
	v_mfma_f32_16x16x32_bf16 v[86:89], v[214:217], v[230:233], v[86:89]
	v_mfma_f32_16x16x32_bf16 v[78:81], v[192:195], v[238:241], v[78:81]
	v_mfma_f32_16x16x32_bf16 v[74:77], v[214:217], v[238:241], v[74:77]
	v_mfma_f32_16x16x32_bf16 v[70:73], v[192:195], v[246:249], v[70:73]
	v_mfma_f32_16x16x32_bf16 v[66:69], v[214:217], v[246:249], v[66:69]
	s_barrier
	s_add_i32 s73, s73, s54
	v_lshl_add_u64 v[154:155], v[154:155], 0, s[26:27]
	s_mov_b32 m0, s73
	ds_read_b128 v[218:221], v156 offset:49152
	ds_read_b128 v[222:225], v156 offset:50176
	ds_read_b128 v[226:229], v156 offset:51200
	ds_read_b128 v[230:233], v156 offset:52224
	ds_read_b128 v[234:237], v156 offset:53248
	ds_read_b128 v[238:241], v156 offset:54272
	ds_read_b128 v[242:245], v156 offset:55296
	ds_read_b128 v[246:249], v156 offset:56320
	global_load_lds_dwordx4 v[154:155], off
	s_add_i32 m0, s73, 0x2000
	s_add_u32 s8, s8, 0x80080
	v_lshl_add_u64 v[154:155], v[162:163], 0, s[26:27]
	s_addc_u32 s9, s9, 0
	s_add_i32 s73, s88, s54
	global_load_lds_dwordx4 v[154:155], off
	v_lshl_add_u64 v[154:155], s[8:9], 0, v[136:137]
	s_mov_b32 m0, s73
	s_nop 0
	global_load_lds_dwordx4 v[154:155], off
	v_lshl_add_u64 v[154:155], s[8:9], 0, v[140:141]
	s_add_i32 m0, s73, 0x2000
	s_nop 0
	global_load_lds_dwordx4 v[154:155], off
	v_lshl_add_u64 v[154:155], v[200:201], 0, s[26:27]
	s_mov_b32 m0, s62
	s_nop 0
	global_load_lds_dwordx4 v[154:155], off
	v_lshl_add_u64 v[154:155], v[250:251], 0, s[26:27]
	s_mov_b32 m0, s63
	s_nop 0
	global_load_lds_dwordx4 v[154:155], off
	s_waitcnt vmcnt(8)
	s_waitcnt lgkmcnt(0)
	s_barrier
	v_mfma_f32_16x16x32_bf16 v[62:65], v[150:153], v[218:221], v[62:65]
	v_mfma_f32_16x16x32_bf16 v[58:61], v[170:173], v[218:221], v[58:61]
	v_mfma_f32_16x16x32_bf16 v[54:57], v[150:153], v[226:229], v[54:57]
	v_mfma_f32_16x16x32_bf16 v[50:53], v[170:173], v[226:229], v[50:53]
	v_mfma_f32_16x16x32_bf16 v[42:45], v[150:153], v[234:237], v[42:45]
	v_mfma_f32_16x16x32_bf16 v[34:37], v[170:173], v[234:237], v[34:37]
	v_mfma_f32_16x16x32_bf16 v[26:29], v[150:153], v[242:245], v[26:29]
	v_mfma_f32_16x16x32_bf16 v[18:21], v[170:173], v[242:245], v[18:21]
	v_mfma_f32_16x16x32_bf16 v[62:65], v[158:161], v[222:225], v[62:65]
	v_mfma_f32_16x16x32_bf16 v[58:61], v[184:187], v[222:225], v[58:61]
	v_mfma_f32_16x16x32_bf16 v[54:57], v[158:161], v[230:233], v[54:57]
	v_mfma_f32_16x16x32_bf16 v[50:53], v[184:187], v[230:233], v[50:53]
	v_mfma_f32_16x16x32_bf16 v[42:45], v[158:161], v[238:241], v[42:45]
	v_mfma_f32_16x16x32_bf16 v[34:37], v[184:187], v[238:241], v[34:37]
	v_mfma_f32_16x16x32_bf16 v[26:29], v[158:161], v[246:249], v[26:29]
	v_mfma_f32_16x16x32_bf16 v[18:21], v[184:187], v[246:249], v[18:21]
	v_mfma_f32_16x16x32_bf16 v[46:49], v[188:191], v[218:221], v[46:49]
	v_mfma_f32_16x16x32_bf16 v[38:41], v[196:199], v[218:221], v[38:41]
	v_mfma_f32_16x16x32_bf16 v[30:33], v[188:191], v[226:229], v[30:33]
	v_mfma_f32_16x16x32_bf16 v[22:25], v[196:199], v[226:229], v[22:25]
	v_mfma_f32_16x16x32_bf16 v[14:17], v[188:191], v[234:237], v[14:17]
	v_mfma_f32_16x16x32_bf16 v[10:13], v[196:199], v[234:237], v[10:13]
	v_mfma_f32_16x16x32_bf16 v[6:9], v[188:191], v[242:245], v[6:9]
	v_mfma_f32_16x16x32_bf16 v[2:5], v[196:199], v[242:245], v[2:5]
	v_mfma_f32_16x16x32_bf16 v[46:49], v[192:195], v[222:225], v[46:49]
	v_mfma_f32_16x16x32_bf16 v[38:41], v[214:217], v[222:225], v[38:41]
	v_mfma_f32_16x16x32_bf16 v[30:33], v[192:195], v[230:233], v[30:33]
	v_mfma_f32_16x16x32_bf16 v[22:25], v[214:217], v[230:233], v[22:25]
	v_mfma_f32_16x16x32_bf16 v[14:17], v[192:195], v[238:241], v[14:17]
	v_mfma_f32_16x16x32_bf16 v[10:13], v[214:217], v[238:241], v[10:13]
	v_mfma_f32_16x16x32_bf16 v[6:9], v[192:195], v[246:249], v[6:9]
	v_mfma_f32_16x16x32_bf16 v[2:5], v[214:217], v[246:249], v[2:5]
	s_barrier
	s_add_u32 s92, s92, 0x100
	s_addc_u32 s93, s93, 0
	s_add_u32 s70, s70, 0x100
	s_addc_u32 s71, s71, 0
	s_cmp_ge_u32 s72, s67
	s_mov_b32 s8, s72
	s_cbranch_scc0 .LBB0_553
	s_and_b64 vcc, exec, s[44:45]
	s_cbranch_vccnz .LBB0_558
	s_cmp_lt_i32 s57, 0
	s_mov_b64 s[8:9], -1
	s_movk_i32 s94, 0x1fff
	s_cbranch_scc1 .LBB0_559

.LBB0_579:
	s_setprio 0
	s_waitcnt vmcnt(0)
	v_readlane_b32 s86, v254, 61
	v_readlane_b32 s84, v255, 0
	v_readlane_b32 s58, v255, 2
	v_readlane_b32 s60, v255, 4
	v_readlane_b32 s62, v255, 6
	v_readlane_b32 s54, v255, 10
	v_readlane_b32 s64, v255, 12
	v_readlane_b32 s92, v255, 14
	v_readlane_b32 s42, v254, 55
	v_readlane_b32 s72, v254, 59
	v_readlane_b32 s73, v254, 60
	v_readlane_b32 s87, v254, 62
	v_readlane_b32 s74, v254, 63
	v_readlane_b32 s85, v255, 1
	v_readlane_b32 s59, v255, 3
	v_readlane_b32 s61, v255, 5
	v_readlane_b32 s63, v255, 7
	v_readlane_b32 s55, v255, 11
	v_readlane_b32 s65, v255, 13
	v_readlane_b32 s93, v255, 15
	v_readlane_b32 s43, v254, 56
	s_barrier

.LBB0_699:
	s_and_b64 vcc, exec, s[38:39]
	s_cbranch_vccnz .LBB0_747
	s_waitcnt lgkmcnt(0)
	v_ashrrev_i32_e32 v2, 31, v16
	v_lshrrev_b32_e32 v2, 26, v2
	v_add_u32_e32 v2, v16, v2
	v_ashrrev_i32_e32 v10, 6, v2
	v_bfe_i32 v2, v16, 27, 1
	v_lshlrev_b32_e32 v1, 4, v16
	v_lshrrev_b32_e32 v2, 22, v2
	v_add_u32_e32 v2, v1, v2
	v_and_b32_e32 v2, 0xfffffc00, v2
	v_sub_u32_e32 v2, v1, v2
	v_lshrrev_b32_e32 v3, 4, v2
	v_bitop3_b32 v2, v3, v2, 32 bitop3:0x6c
	v_ashrrev_i32_e32 v4, 31, v2
	v_lshrrev_b32_e32 v4, 26, v4
	v_add_u32_e32 v4, v2, v4
	v_lshlrev_b32_e32 v3, 3, v10
	v_ashrrev_i32_e32 v11, 6, v4
	v_and_b32_e32 v4, 0xc0, v4
	v_and_b32_e32 v3, -16, v3
	v_sub_u32_e32 v2, v2, v4
	v_add_u32_e32 v3, v11, v3
	v_ashrrev_i16_sdwa v2, v211, sext(v2) dst_sel:DWORD dst_unused:UNUSED_PAD src0_sel:DWORD src1_sel:BYTE_0
	v_lshlrev_b32_e32 v5, 5, v10
	v_bfe_i32 v12, v2, 0, 16
	v_lshlrev_b32_e32 v2, 1, v3
	v_lshrrev_b32_e32 v4, 2, v3
	v_and_b32_e32 v6, 3, v11
	s_mov_b32 s4, 0xfffe0
	v_and_b32_e32 v5, 32, v5
	v_and_b32_e32 v2, 24, v2
	v_and_b32_e32 v4, 4, v4
	v_and_or_b32 v6, v3, s4, v6
	v_or3_b32 v2, v6, v4, v2
	v_add_lshl_u32 v4, v5, v12, 1
	v_add_u32_e32 v1, 0x2000, v1
	s_waitcnt vmcnt(0)
	v_lshl_add_u32 v136, v2, 12, v4
	v_ashrrev_i32_e32 v2, 31, v1
	v_lshrrev_b32_e32 v2, 22, v2
	v_add_u32_e32 v2, v1, v2
	v_ashrrev_i32_e32 v13, 10, v2
	v_mul_i32_i24_e32 v2, 0x400, v13
	v_sub_u32_e32 v1, v1, v2
	v_lshrrev_b32_e32 v2, 4, v1
	v_bitop3_b32 v1, v2, v1, 32 bitop3:0x6c
	v_lshl_add_u32 v110, v3, 12, v4
	v_ashrrev_i32_e32 v3, 31, v1
	v_lshrrev_b32_e32 v3, 26, v3
	v_lshlrev_b32_e32 v2, 3, v13
	v_add_u32_e32 v3, v1, v3
	v_and_b32_e32 v2, -16, v2
	v_ashrrev_i32_e32 v14, 6, v3
	v_add_u32_e32 v2, v14, v2
	v_and_b32_e32 v5, 3, v14
	v_and_or_b32 v5, v2, s4, v5
	s_ashr_i32 s7, s16, 6
	v_readlane_b32 s4, v254, 57
	s_ashr_i32 s6, s16, 8
	s_lshl_b32 s54, s7, 10
	v_readlane_b32 s5, v254, 58
	s_and_b64 s[4:5], s[4:5], exec
	v_readlane_b32 s4, v252, 47
	v_readlane_b32 s8, v252, 55
	v_readlane_b32 s5, v252, 48
	v_readlane_b32 s9, v252, 56
	v_and_b32_e32 v3, 0xc0, v3
	s_cselect_b32 s55, s5, s9
	s_cselect_b32 s56, s4, s8
	s_ashr_i32 s85, s84, 31
	s_ashr_i32 s41, s40, 31
	v_sub_u32_e32 v1, v1, v3
	s_lshl_b64 s[4:5], s[84:85], 20
	s_lshl_b64 s[8:9], s[40:41], 20
	v_ashrrev_i16_sdwa v1, v211, sext(v1) dst_sel:DWORD dst_unused:UNUSED_PAD src0_sel:DWORD src1_sel:BYTE_0
	s_add_u32 s8, s56, s8
	v_lshlrev_b32_e32 v4, 5, v13
	v_bfe_i32 v15, v1, 0, 16
	v_lshlrev_b32_e32 v1, 1, v2
	v_lshrrev_b32_e32 v3, 2, v2
	s_addc_u32 s9, s55, s9
	s_add_i32 s57, s54, 0
	v_and_b32_e32 v4, 32, v4
	v_and_b32_e32 v1, 24, v1
	v_and_b32_e32 v3, 4, v3
	s_add_i32 m0, s57, 0x10000
	v_or3_b32 v1, v5, v3, v1
	v_add_lshl_u32 v3, v4, v15, 1
	global_load_lds_dwordx4 v136, s[8:9]
	s_add_i32 m0, s57, 0x12000
	v_lshl_add_u32 v140, v1, 12, v3
	s_add_u32 s38, s8, 0x80000
	global_load_lds_dwordx4 v140, s[8:9]
	s_addc_u32 s39, s9, 0
	s_add_i32 m0, s57, 0x14000
	v_lshl_add_u32 v138, v2, 12, v3
	global_load_lds_dwordx4 v136, s[38:39]
	s_add_i32 m0, s57, 0x16000
	s_add_u32 s86, s80, s4
	s_addc_u32 s87, s81, s5
	s_add_i32 s58, s57, 0x2000
	global_load_lds_dwordx4 v140, s[38:39]
	s_mov_b32 m0, s57
	s_add_u32 s4, s86, 0x80000
	global_load_lds_dwordx4 v110, s[86:87]
	s_mov_b32 m0, s58
	s_addc_u32 s5, s87, 0
	s_add_i32 s59, s57, 0x4000
	global_load_lds_dwordx4 v138, s[86:87]
	s_mov_b32 m0, s59
	s_add_i32 s60, s57, 0x6000
	global_load_lds_dwordx4 v110, s[4:5]
	s_mov_b32 m0, s60
	v_mov_b32_e32 v137, v0
	global_load_lds_dwordx4 v138, s[4:5]
	v_mov_b32_e32 v141, v0
	v_mov_b32_e32 v111, v0
	v_mov_b32_e32 v139, v0
	s_cmp_eq_u32 s6, 1
	v_lshl_add_u64 v[8:9], s[8:9], 0, v[136:137]
	v_lshl_add_u64 v[6:7], s[8:9], 0, v[140:141]
	v_lshl_add_u64 v[2:3], s[86:87], 0, v[110:111]
	s_cselect_b64 s[4:5], -1, 0
	s_cmp_lg_u32 s6, 1
	v_lshl_add_u64 v[4:5], s[86:87], 0, v[138:139]
	s_cbranch_scc1 .LBB0_702
	s_barrier
	s_setprio 1

.LBB0_708:
	s_add_u32 s8, s86, 0xfff80080
	s_addc_u32 s9, s87, -1
	s_add_i32 s67, 0, 0x10000
	s_cmp_eq_u32 s66, 28
	s_cselect_b32 s93, s41, s9
	s_cselect_b32 s92, s45, s8
	v_add_u32_e32 v150, s67, v152
	s_cselect_b32 s9, s43, s65
	s_cselect_b32 s8, s63, s64
	s_add_i32 s70, 0, 0x14000
	ds_read_b128 v[146:149], v150
	ds_read_b128 v[156:159], v150 offset:1024
	ds_read_b128 v[160:163], v150 offset:2048
	ds_read_b128 v[170:173], v150 offset:3072
	v_add_u32_e32 v150, s70, v152
	ds_read_b128 v[184:187], v150
	ds_read_b128 v[188:191], v150 offset:1024
	ds_read_b128 v[192:195], v150 offset:2048
	ds_read_b128 v[196:199], v150 offset:3072
	v_lshl_add_u64 v[150:151], s[86:87], 0, v[142:143]
	s_add_i32 m0, s57, 0xc000
	ds_read_b128 v[214:217], v154
	ds_read_b128 v[218:221], v154 offset:1024
	ds_read_b128 v[222:225], v154 offset:2048
	ds_read_b128 v[226:229], v154 offset:3072
	ds_read_b128 v[230:233], v154 offset:4096
	ds_read_b128 v[234:237], v154 offset:5120
	ds_read_b128 v[238:241], v154 offset:6144
	ds_read_b128 v[242:245], v154 offset:7168
	global_load_lds_dwordx4 v[150:151], off
	v_lshl_add_u64 v[150:151], s[86:87], 0, v[144:145]
	s_add_i32 m0, s57, 0xe000
	s_nop 0
	global_load_lds_dwordx4 v[150:151], off
	s_waitcnt vmcnt(8)
	s_waitcnt lgkmcnt(0)
	s_barrier
	v_mfma_f32_16x16x32_bf16 v[132:135], v[146:149], v[214:217], v[132:135]
	v_mfma_f32_16x16x32_bf16 v[128:131], v[160:163], v[214:217], v[128:131]
	v_mfma_f32_16x16x32_bf16 v[116:119], v[146:149], v[222:225], v[116:119]
	v_mfma_f32_16x16x32_bf16 v[106:109], v[160:163], v[222:225], v[106:109]
	v_mfma_f32_16x16x32_bf16 v[94:97], v[146:149], v[230:233], v[94:97]
	v_mfma_f32_16x16x32_bf16 v[90:93], v[160:163], v[230:233], v[90:93]
	v_mfma_f32_16x16x32_bf16 v[78:81], v[146:149], v[238:241], v[78:81]
	v_mfma_f32_16x16x32_bf16 v[74:77], v[160:163], v[238:241], v[74:77]
	v_mfma_f32_16x16x32_bf16 v[132:135], v[156:159], v[218:221], v[132:135]
	v_mfma_f32_16x16x32_bf16 v[128:131], v[170:173], v[218:221], v[128:131]
	v_mfma_f32_16x16x32_bf16 v[116:119], v[156:159], v[226:229], v[116:119]
	v_mfma_f32_16x16x32_bf16 v[106:109], v[170:173], v[226:229], v[106:109]
	v_mfma_f32_16x16x32_bf16 v[94:97], v[156:159], v[234:237], v[94:97]
	v_mfma_f32_16x16x32_bf16 v[90:93], v[170:173], v[234:237], v[90:93]
	v_mfma_f32_16x16x32_bf16 v[78:81], v[156:159], v[242:245], v[78:81]
	v_mfma_f32_16x16x32_bf16 v[74:77], v[170:173], v[242:245], v[74:77]
	v_mfma_f32_16x16x32_bf16 v[124:127], v[184:187], v[214:217], v[124:127]
	v_mfma_f32_16x16x32_bf16 v[120:123], v[192:195], v[214:217], v[120:123]
	v_mfma_f32_16x16x32_bf16 v[102:105], v[184:187], v[222:225], v[102:105]
	v_mfma_f32_16x16x32_bf16 v[98:101], v[192:195], v[222:225], v[98:101]
	v_mfma_f32_16x16x32_bf16 v[86:89], v[184:187], v[230:233], v[86:89]
	v_mfma_f32_16x16x32_bf16 v[82:85], v[192:195], v[230:233], v[82:85]
	v_mfma_f32_16x16x32_bf16 v[70:73], v[184:187], v[238:241], v[70:73]
	v_mfma_f32_16x16x32_bf16 v[66:69], v[192:195], v[238:241], v[66:69]
	v_mfma_f32_16x16x32_bf16 v[124:127], v[188:191], v[218:221], v[124:127]
	v_mfma_f32_16x16x32_bf16 v[120:123], v[196:199], v[218:221], v[120:123]
	v_mfma_f32_16x16x32_bf16 v[102:105], v[188:191], v[226:229], v[102:105]
	v_mfma_f32_16x16x32_bf16 v[98:101], v[196:199], v[226:229], v[98:101]
	v_mfma_f32_16x16x32_bf16 v[86:89], v[188:191], v[234:237], v[86:89]
	v_mfma_f32_16x16x32_bf16 v[82:85], v[196:199], v[234:237], v[82:85]
	v_mfma_f32_16x16x32_bf16 v[70:73], v[188:191], v[242:245], v[70:73]
	v_mfma_f32_16x16x32_bf16 v[66:69], v[196:199], v[242:245], v[66:69]
	s_barrier
	s_add_i32 s67, s67, s54
	v_lshl_add_u64 v[150:151], s[8:9], 0, v[136:137]
	s_mov_b32 m0, s67
	ds_read_b128 v[214:217], v154 offset:16384
	ds_read_b128 v[218:221], v154 offset:17408
	ds_read_b128 v[222:225], v154 offset:18432
	ds_read_b128 v[226:229], v154 offset:19456
	ds_read_b128 v[230:233], v154 offset:20480
	ds_read_b128 v[234:237], v154 offset:21504
	ds_read_b128 v[238:241], v154 offset:22528
	ds_read_b128 v[242:245], v154 offset:23552
	global_load_lds_dwordx4 v[150:151], off
	s_add_i32 m0, s67, 0x2000
	s_add_u32 s68, s8, 0x80000
	v_lshl_add_u64 v[200:201], s[8:9], 0, v[140:141]
	s_addc_u32 s69, s9, 0
	s_add_i32 s67, s70, s54
	global_load_lds_dwordx4 v[200:201], off
	v_lshl_add_u64 v[206:207], s[68:69], 0, v[136:137]
	s_mov_b32 m0, s67
	v_lshl_add_u64 v[246:247], s[92:93], 0, v[138:139]
	global_load_lds_dwordx4 v[206:207], off
	v_lshl_add_u64 v[206:207], s[68:69], 0, v[140:141]
	s_add_i32 m0, s67, 0x2000
	s_nop 0
	global_load_lds_dwordx4 v[206:207], off
	v_lshl_add_u64 v[206:207], s[92:93], 0, v[110:111]
	s_mov_b32 m0, s57
	s_nop 0
	global_load_lds_dwordx4 v[206:207], off
	s_mov_b32 m0, s58
	s_nop 0
	global_load_lds_dwordx4 v[246:247], off
	s_waitcnt vmcnt(8)
	s_waitcnt lgkmcnt(0)
	s_barrier
	v_mfma_f32_16x16x32_bf16 v[62:65], v[146:149], v[214:217], v[62:65]
	v_mfma_f32_16x16x32_bf16 v[58:61], v[160:163], v[214:217], v[58:61]
	v_mfma_f32_16x16x32_bf16 v[46:49], v[146:149], v[222:225], v[46:49]
	v_mfma_f32_16x16x32_bf16 v[42:45], v[160:163], v[222:225], v[42:45]
	v_mfma_f32_16x16x32_bf16 v[30:33], v[146:149], v[230:233], v[30:33]
	v_mfma_f32_16x16x32_bf16 v[26:29], v[160:163], v[230:233], v[26:29]
	v_mfma_f32_16x16x32_bf16 v[14:17], v[146:149], v[238:241], v[14:17]
	v_mfma_f32_16x16x32_bf16 v[10:13], v[160:163], v[238:241], v[10:13]
	v_mfma_f32_16x16x32_bf16 v[62:65], v[156:159], v[218:221], v[62:65]
	v_mfma_f32_16x16x32_bf16 v[58:61], v[170:173], v[218:221], v[58:61]
	v_mfma_f32_16x16x32_bf16 v[46:49], v[156:159], v[226:229], v[46:49]
	v_mfma_f32_16x16x32_bf16 v[42:45], v[170:173], v[226:229], v[42:45]
	v_mfma_f32_16x16x32_bf16 v[30:33], v[156:159], v[234:237], v[30:33]
	v_mfma_f32_16x16x32_bf16 v[26:29], v[170:173], v[234:237], v[26:29]
	v_mfma_f32_16x16x32_bf16 v[14:17], v[156:159], v[242:245], v[14:17]
	v_mfma_f32_16x16x32_bf16 v[10:13], v[170:173], v[242:245], v[10:13]
	v_mfma_f32_16x16x32_bf16 v[54:57], v[184:187], v[214:217], v[54:57]
	v_mfma_f32_16x16x32_bf16 v[50:53], v[192:195], v[214:217], v[50:53]
	v_mfma_f32_16x16x32_bf16 v[38:41], v[184:187], v[222:225], v[38:41]
	v_mfma_f32_16x16x32_bf16 v[34:37], v[192:195], v[222:225], v[34:37]
	v_mfma_f32_16x16x32_bf16 v[22:25], v[184:187], v[230:233], v[22:25]
	v_mfma_f32_16x16x32_bf16 v[18:21], v[192:195], v[230:233], v[18:21]
	v_mfma_f32_16x16x32_bf16 v[6:9], v[184:187], v[238:241], v[6:9]
	v_mfma_f32_16x16x32_bf16 v[2:5], v[192:195], v[238:241], v[2:5]
	v_mfma_f32_16x16x32_bf16 v[54:57], v[188:191], v[218:221], v[54:57]
	v_mfma_f32_16x16x32_bf16 v[50:53], v[196:199], v[218:221], v[50:53]
	v_mfma_f32_16x16x32_bf16 v[38:41], v[188:191], v[226:229], v[38:41]
	v_mfma_f32_16x16x32_bf16 v[34:37], v[196:199], v[226:229], v[34:37]
	v_mfma_f32_16x16x32_bf16 v[22:25], v[188:191], v[234:237], v[22:25]
	v_mfma_f32_16x16x32_bf16 v[18:21], v[196:199], v[234:237], v[18:21]
	v_mfma_f32_16x16x32_bf16 v[6:9], v[188:191], v[242:245], v[6:9]
	v_mfma_f32_16x16x32_bf16 v[2:5], v[196:199], v[242:245], v[2:5]
	s_barrier
	s_add_i32 s67, 0, 0x18000
	v_add_u32_e32 v155, s67, v152
	s_add_i32 s70, 0, 0x1c000
	ds_read_b128 v[146:149], v155
	ds_read_b128 v[156:159], v155 offset:1024
	ds_read_b128 v[160:163], v155 offset:2048
	ds_read_b128 v[170:173], v155 offset:3072
	v_add_u32_e32 v155, s70, v152
	ds_read_b128 v[184:187], v155
	ds_read_b128 v[188:191], v155 offset:1024
	ds_read_b128 v[192:195], v155 offset:2048
	ds_read_b128 v[196:199], v155 offset:3072
	s_add_u32 s68, s92, 0x80000
	s_addc_u32 s69, s93, 0
	s_mov_b32 m0, s59
	v_lshl_add_u64 v[248:249], s[68:69], 0, v[110:111]
	ds_read_b128 v[214:217], v154 offset:32768
	ds_read_b128 v[218:221], v154 offset:33792
	ds_read_b128 v[222:225], v154 offset:34816
	ds_read_b128 v[226:229], v154 offset:35840
	ds_read_b128 v[230:233], v154 offset:36864
	ds_read_b128 v[234:237], v154 offset:37888
	ds_read_b128 v[238:241], v154 offset:38912
	ds_read_b128 v[242:245], v154 offset:39936
	global_load_lds_dwordx4 v[248:249], off
	v_lshl_add_u64 v[248:249], s[68:69], 0, v[138:139]
	s_mov_b32 m0, s60
	s_nop 0
	global_load_lds_dwordx4 v[248:249], off
	s_waitcnt vmcnt(8)
	s_waitcnt lgkmcnt(0)
	s_barrier
	v_mfma_f32_16x16x32_bf16 v[132:135], v[146:149], v[214:217], v[132:135]
	v_mfma_f32_16x16x32_bf16 v[128:131], v[160:163], v[214:217], v[128:131]
	v_mfma_f32_16x16x32_bf16 v[116:119], v[146:149], v[222:225], v[116:119]
	v_mfma_f32_16x16x32_bf16 v[106:109], v[160:163], v[222:225], v[106:109]
	v_mfma_f32_16x16x32_bf16 v[94:97], v[146:149], v[230:233], v[94:97]
	v_mfma_f32_16x16x32_bf16 v[90:93], v[160:163], v[230:233], v[90:93]
	v_mfma_f32_16x16x32_bf16 v[78:81], v[146:149], v[238:241], v[78:81]
	v_mfma_f32_16x16x32_bf16 v[74:77], v[160:163], v[238:241], v[74:77]
	v_mfma_f32_16x16x32_bf16 v[132:135], v[156:159], v[218:221], v[132:135]
	v_mfma_f32_16x16x32_bf16 v[128:131], v[170:173], v[218:221], v[128:131]
	v_mfma_f32_16x16x32_bf16 v[116:119], v[156:159], v[226:229], v[116:119]
	v_mfma_f32_16x16x32_bf16 v[106:109], v[170:173], v[226:229], v[106:109]
	v_mfma_f32_16x16x32_bf16 v[94:97], v[156:159], v[234:237], v[94:97]
	v_mfma_f32_16x16x32_bf16 v[90:93], v[170:173], v[234:237], v[90:93]
	v_mfma_f32_16x16x32_bf16 v[78:81], v[156:159], v[242:245], v[78:81]
	v_mfma_f32_16x16x32_bf16 v[74:77], v[170:173], v[242:245], v[74:77]
	v_mfma_f32_16x16x32_bf16 v[124:127], v[184:187], v[214:217], v[124:127]
	v_mfma_f32_16x16x32_bf16 v[120:123], v[192:195], v[214:217], v[120:123]
	v_mfma_f32_16x16x32_bf16 v[102:105], v[184:187], v[222:225], v[102:105]
	v_mfma_f32_16x16x32_bf16 v[98:101], v[192:195], v[222:225], v[98:101]
	v_mfma_f32_16x16x32_bf16 v[86:89], v[184:187], v[230:233], v[86:89]
	v_mfma_f32_16x16x32_bf16 v[82:85], v[192:195], v[230:233], v[82:85]
	v_mfma_f32_16x16x32_bf16 v[70:73], v[184:187], v[238:241], v[70:73]
	v_mfma_f32_16x16x32_bf16 v[66:69], v[192:195], v[238:241], v[66:69]
	v_mfma_f32_16x16x32_bf16 v[124:127], v[188:191], v[218:221], v[124:127]
	v_mfma_f32_16x16x32_bf16 v[120:123], v[196:199], v[218:221], v[120:123]
	v_mfma_f32_16x16x32_bf16 v[102:105], v[188:191], v[226:229], v[102:105]
	v_mfma_f32_16x16x32_bf16 v[98:101], v[196:199], v[226:229], v[98:101]
	v_mfma_f32_16x16x32_bf16 v[86:89], v[188:191], v[234:237], v[86:89]
	v_mfma_f32_16x16x32_bf16 v[82:85], v[196:199], v[234:237], v[82:85]
	v_mfma_f32_16x16x32_bf16 v[70:73], v[188:191], v[242:245], v[70:73]
	v_mfma_f32_16x16x32_bf16 v[66:69], v[196:199], v[242:245], v[66:69]
	s_barrier
	s_add_i32 s67, s67, s54
	v_lshl_add_u64 v[150:151], v[150:151], 0, s[26:27]
	s_mov_b32 m0, s67
	ds_read_b128 v[214:217], v154 offset:49152
	ds_read_b128 v[218:221], v154 offset:50176
	ds_read_b128 v[222:225], v154 offset:51200
	ds_read_b128 v[226:229], v154 offset:52224
	ds_read_b128 v[230:233], v154 offset:53248
	ds_read_b128 v[234:237], v154 offset:54272
	ds_read_b128 v[238:241], v154 offset:55296
	ds_read_b128 v[242:245], v154 offset:56320
	global_load_lds_dwordx4 v[150:151], off
	s_add_i32 m0, s67, 0x2000
	s_add_u32 s8, s8, 0x80080
	v_lshl_add_u64 v[150:151], v[200:201], 0, s[26:27]
	s_addc_u32 s9, s9, 0
	s_add_i32 s67, s70, s54
	global_load_lds_dwordx4 v[150:151], off
	v_lshl_add_u64 v[150:151], s[8:9], 0, v[136:137]
	s_mov_b32 m0, s67
	s_nop 0
	global_load_lds_dwordx4 v[150:151], off
	v_lshl_add_u64 v[150:151], s[8:9], 0, v[140:141]
	s_add_i32 m0, s67, 0x2000
	s_nop 0
	global_load_lds_dwordx4 v[150:151], off
	v_lshl_add_u64 v[150:151], v[206:207], 0, s[26:27]
	s_mov_b32 m0, s37
	s_nop 0
	global_load_lds_dwordx4 v[150:151], off
	v_lshl_add_u64 v[150:151], v[246:247], 0, s[26:27]
	s_mov_b32 m0, s61
	s_nop 0
	global_load_lds_dwordx4 v[150:151], off
	s_waitcnt vmcnt(8)
	s_waitcnt lgkmcnt(0)
	s_barrier
	v_mfma_f32_16x16x32_bf16 v[62:65], v[146:149], v[214:217], v[62:65]
	v_mfma_f32_16x16x32_bf16 v[58:61], v[160:163], v[214:217], v[58:61]
	v_mfma_f32_16x16x32_bf16 v[46:49], v[146:149], v[222:225], v[46:49]
	v_mfma_f32_16x16x32_bf16 v[42:45], v[160:163], v[222:225], v[42:45]
	v_mfma_f32_16x16x32_bf16 v[30:33], v[146:149], v[230:233], v[30:33]
	v_mfma_f32_16x16x32_bf16 v[26:29], v[160:163], v[230:233], v[26:29]
	v_mfma_f32_16x16x32_bf16 v[14:17], v[146:149], v[238:241], v[14:17]
	v_mfma_f32_16x16x32_bf16 v[10:13], v[160:163], v[238:241], v[10:13]
	v_mfma_f32_16x16x32_bf16 v[62:65], v[156:159], v[218:221], v[62:65]
	v_mfma_f32_16x16x32_bf16 v[58:61], v[170:173], v[218:221], v[58:61]
	v_mfma_f32_16x16x32_bf16 v[46:49], v[156:159], v[226:229], v[46:49]
	v_mfma_f32_16x16x32_bf16 v[42:45], v[170:173], v[226:229], v[42:45]
	v_mfma_f32_16x16x32_bf16 v[30:33], v[156:159], v[234:237], v[30:33]
	v_mfma_f32_16x16x32_bf16 v[26:29], v[170:173], v[234:237], v[26:29]
	v_mfma_f32_16x16x32_bf16 v[14:17], v[156:159], v[242:245], v[14:17]
	v_mfma_f32_16x16x32_bf16 v[10:13], v[170:173], v[242:245], v[10:13]
	v_mfma_f32_16x16x32_bf16 v[54:57], v[184:187], v[214:217], v[54:57]
	v_mfma_f32_16x16x32_bf16 v[50:53], v[192:195], v[214:217], v[50:53]
	v_mfma_f32_16x16x32_bf16 v[38:41], v[184:187], v[222:225], v[38:41]
	v_mfma_f32_16x16x32_bf16 v[34:37], v[192:195], v[222:225], v[34:37]
	v_mfma_f32_16x16x32_bf16 v[22:25], v[184:187], v[230:233], v[22:25]
	v_mfma_f32_16x16x32_bf16 v[18:21], v[192:195], v[230:233], v[18:21]
	v_mfma_f32_16x16x32_bf16 v[6:9], v[184:187], v[238:241], v[6:9]
	v_mfma_f32_16x16x32_bf16 v[2:5], v[192:195], v[238:241], v[2:5]
	v_mfma_f32_16x16x32_bf16 v[54:57], v[188:191], v[218:221], v[54:57]
	v_mfma_f32_16x16x32_bf16 v[50:53], v[196:199], v[218:221], v[50:53]
	v_mfma_f32_16x16x32_bf16 v[38:41], v[188:191], v[226:229], v[38:41]
	v_mfma_f32_16x16x32_bf16 v[34:37], v[196:199], v[226:229], v[34:37]
	v_mfma_f32_16x16x32_bf16 v[22:25], v[188:191], v[234:237], v[22:25]
	v_mfma_f32_16x16x32_bf16 v[18:21], v[196:199], v[234:237], v[18:21]
	v_mfma_f32_16x16x32_bf16 v[6:9], v[188:191], v[242:245], v[6:9]
	v_mfma_f32_16x16x32_bf16 v[2:5], v[196:199], v[242:245], v[2:5]
	s_barrier
	s_add_i32 s66, s66, 2
	s_add_u32 s86, s86, 0x100
	s_addc_u32 s87, s87, 0
	s_add_u32 s64, s64, 0x100
	s_addc_u32 s65, s65, 0
	s_cmp_gt_u32 s66, 29
	s_cbranch_scc0 .LBB0_708
	s_and_b64 vcc, exec, s[16:17]
	s_cbranch_vccz .LBB0_711
	s_barrier

.LBB0_746:
	s_setprio 0
	s_waitcnt vmcnt(0)
	v_readlane_b32 s86, v254, 61
	v_readlane_b32 s58, v255, 2
	v_readlane_b32 s60, v255, 4
	v_readlane_b32 s62, v255, 6
	v_readlane_b32 s56, v255, 8
	v_readlane_b32 s54, v255, 10
	v_readlane_b32 s46, v254, 55
	v_readlane_b32 s72, v254, 59
	v_readlane_b32 s73, v254, 60
	v_readlane_b32 s87, v254, 62
	v_readlane_b32 s59, v255, 3
	v_readlane_b32 s61, v255, 5
	v_readlane_b32 s63, v255, 7
	v_readlane_b32 s57, v255, 9
	v_readlane_b32 s55, v255, 11
	v_readlane_b32 s47, v254, 56
	s_barrier

.LBB0_839:
	v_readlane_b32 s4, v254, 57
	v_readlane_b32 s5, v254, 58
	s_and_b64 s[4:5], s[4:5], exec
	v_readlane_b32 s4, v252, 44
	v_readlane_b32 s5, v252, 42
	s_cselect_b32 s5, s5, s4
	v_readlane_b32 s4, v252, 43
	v_readlane_b32 s7, v252, 41
	s_cselect_b32 s4, s7, s4
	s_and_b64 vcc, exec, s[38:39]
	s_cbranch_vccnz .LBB0_880
	v_ashrrev_i32_e32 v3, 31, v1
	v_lshrrev_b32_e32 v3, 26, v3
	v_add_u32_e32 v3, v1, v3
	v_ashrrev_i32_e32 v10, 6, v3
	v_bfe_i32 v3, v1, 27, 1
	v_lshlrev_b32_e32 v2, 4, v1
	v_lshrrev_b32_e32 v3, 22, v3
	v_add_u32_e32 v3, v2, v3
	v_and_b32_e32 v3, 0xfffffc00, v3
	v_sub_u32_e32 v3, v2, v3
	v_lshrrev_b32_e32 v4, 4, v3
	v_bitop3_b32 v3, v4, v3, 32 bitop3:0x6c
	v_ashrrev_i32_e32 v5, 31, v3
	v_lshrrev_b32_e32 v5, 26, v5
	v_add_u32_e32 v5, v3, v5
	v_lshlrev_b32_e32 v4, 3, v10
	v_ashrrev_i32_e32 v11, 6, v5
	v_and_b32_e32 v5, 0xc0, v5
	v_and_b32_e32 v4, -16, v4
	v_sub_u32_e32 v3, v3, v5
	v_add_u32_e32 v4, v11, v4
	v_ashrrev_i16_sdwa v3, v211, sext(v3) dst_sel:DWORD dst_unused:UNUSED_PAD src0_sel:DWORD src1_sel:BYTE_0
	v_lshlrev_b32_e32 v6, 5, v10
	v_bfe_i32 v12, v3, 0, 16
	v_lshlrev_b32_e32 v3, 1, v4
	v_lshrrev_b32_e32 v5, 2, v4
	v_and_b32_e32 v7, 3, v11
	s_mov_b32 s7, 0x3ffe0
	v_and_b32_e32 v6, 32, v6
	v_and_b32_e32 v3, 24, v3
	v_and_b32_e32 v5, 4, v5
	v_and_or_b32 v7, v4, s7, v7
	v_or3_b32 v3, v7, v5, v3
	v_add_lshl_u32 v5, v6, v12, 1
	v_add_u32_e32 v2, 0x2000, v2
	s_waitcnt vmcnt(0)
	v_lshl_add_u32 v136, v3, 14, v5
	v_ashrrev_i32_e32 v3, 31, v2
	v_lshrrev_b32_e32 v3, 22, v3
	v_add_u32_e32 v3, v2, v3
	v_ashrrev_i32_e32 v13, 10, v3
	v_mul_i32_i24_e32 v3, 0x400, v13
	s_ashr_i32 s38, s40, 6
	v_sub_u32_e32 v2, v2, v3
	v_readlane_b32 s8, v254, 57
	v_lshrrev_b32_e32 v3, 4, v2
	s_ashr_i32 s39, s40, 8
	s_lshl_b32 s37, s38, 10
	v_readlane_b32 s9, v254, 58
	v_bitop3_b32 v2, v3, v2, 32 bitop3:0x6c
	s_and_b64 s[8:9], s[8:9], exec
	v_lshl_add_u32 v110, v4, 14, v5
	v_ashrrev_i32_e32 v4, 31, v2
	v_readlane_b32 s8, v252, 49
	v_readlane_b32 s42, v252, 57
	v_lshrrev_b32_e32 v4, 26, v4
	v_readlane_b32 s9, v252, 50
	v_readlane_b32 s43, v252, 58
	v_lshlrev_b32_e32 v3, 3, v13
	v_add_u32_e32 v4, v2, v4
	s_cselect_b32 s54, s9, s43
	s_cselect_b32 s55, s8, s42
	s_ashr_i32 s17, s16, 31
	v_and_b32_e32 v3, -16, v3
	v_ashrrev_i32_e32 v14, 6, v4
	s_lshl_b64 s[8:9], s[16:17], 22
	v_add_u32_e32 v3, v14, v3
	v_and_b32_e32 v6, 3, v14
	s_add_u32 s41, s10, s8
	v_and_or_b32 v6, v3, s7, v6
	s_addc_u32 s44, s11, s9
	s_ashr_i32 s7, s6, 31
	s_lshl_b64 s[8:9], s[6:7], 22
	v_and_b32_e32 v4, 0xc0, v4
	s_add_u32 s7, s55, s8
	v_sub_u32_e32 v2, v2, v4
	s_addc_u32 s9, s54, s9
	v_ashrrev_i16_sdwa v2, v211, sext(v2) dst_sel:DWORD dst_unused:UNUSED_PAD src0_sel:DWORD src1_sel:BYTE_0
	s_add_u32 s8, s7, s34
	v_lshlrev_b32_e32 v5, 5, v13
	v_bfe_i32 v15, v2, 0, 16
	v_lshlrev_b32_e32 v2, 1, v3
	v_lshrrev_b32_e32 v4, 2, v3
	s_addc_u32 s9, s9, s35
	s_add_i32 s17, s37, 0
	v_and_b32_e32 v5, 32, v5
	v_and_b32_e32 v2, 24, v2
	v_and_b32_e32 v4, 4, v4
	s_add_i32 m0, s17, 0x10000
	v_or3_b32 v2, v6, v4, v2
	v_add_lshl_u32 v4, v5, v15, 1
	global_load_lds_dwordx4 v136, s[8:9]
	s_add_i32 m0, s17, 0x12000
	v_lshl_add_u32 v140, v2, 14, v4
	s_add_u32 s42, s8, 0x200000
	global_load_lds_dwordx4 v140, s[8:9]
	s_addc_u32 s43, s9, 0
	s_add_i32 m0, s17, 0x14000
	v_lshl_add_u32 v138, v3, 14, v4
	global_load_lds_dwordx4 v136, s[42:43]
	s_add_i32 m0, s17, 0x16000
	s_add_u32 s86, s41, s34
	s_addc_u32 s87, s44, s35
	s_add_i32 s57, s17, 0x2000
	global_load_lds_dwordx4 v140, s[42:43]
	s_mov_b32 m0, s17
	s_add_u32 s34, s86, 0x200000
	global_load_lds_dwordx4 v110, s[86:87]
	s_mov_b32 m0, s57
	s_addc_u32 s35, s87, 0
	s_add_i32 s58, s17, 0x4000
	global_load_lds_dwordx4 v138, s[86:87]
	s_mov_b32 m0, s58
	s_add_i32 s59, s17, 0x6000
	global_load_lds_dwordx4 v110, s[34:35]
	s_mov_b32 m0, s59
	v_mov_b32_e32 v137, v0
	global_load_lds_dwordx4 v138, s[34:35]
	v_mov_b32_e32 v141, v0
	v_mov_b32_e32 v111, v0
	v_mov_b32_e32 v139, v0
	s_cmp_eq_u32 s39, 1
	v_lshl_add_u64 v[8:9], s[8:9], 0, v[136:137]
	v_lshl_add_u64 v[6:7], s[8:9], 0, v[140:141]
	v_lshl_add_u64 v[2:3], s[86:87], 0, v[110:111]
	s_cselect_b64 s[34:35], -1, 0
	s_cmp_lg_u32 s39, 1
	v_lshl_add_u64 v[4:5], s[86:87], 0, v[138:139]
	s_cbranch_scc1 .LBB0_842
	s_barrier
	s_setprio 1

.LBB0_853:
	s_add_i32 s71, s8, 2
	s_add_u32 s9, s86, 0xffe00080
	s_addc_u32 s72, s87, -1
	s_add_i32 s73, 0, 0x10000
	s_cmp_eq_u32 s68, s8
	s_cselect_b32 s93, s7, s72
	s_cselect_b32 s92, s47, s9
	v_add_u32_e32 v154, s73, v1
	s_cselect_b32 s9, s45, s70
	s_cselect_b32 s8, s67, s69
	s_add_i32 s74, 0, 0x14000
	s_waitcnt lgkmcnt(0)
	ds_read_b128 v[150:153], v154
	ds_read_b128 v[158:161], v154 offset:1024
	ds_read_b128 v[170:173], v154 offset:2048
	ds_read_b128 v[184:187], v154 offset:3072
	v_add_u32_e32 v154, s74, v1
	ds_read_b128 v[188:191], v154
	ds_read_b128 v[192:195], v154 offset:1024
	ds_read_b128 v[196:199], v154 offset:2048
	ds_read_b128 v[214:217], v154 offset:3072
	v_lshl_add_u64 v[154:155], s[86:87], 0, v[146:147]
	s_add_i32 m0, s17, 0xc000
	ds_read_b128 v[218:221], v156
	ds_read_b128 v[222:225], v156 offset:1024
	ds_read_b128 v[226:229], v156 offset:2048
	ds_read_b128 v[230:233], v156 offset:3072
	ds_read_b128 v[234:237], v156 offset:4096
	ds_read_b128 v[238:241], v156 offset:5120
	ds_read_b128 v[242:245], v156 offset:6144
	ds_read_b128 v[246:249], v156 offset:7168
	global_load_lds_dwordx4 v[154:155], off
	v_lshl_add_u64 v[154:155], s[86:87], 0, v[148:149]
	s_add_i32 m0, s17, 0xe000
	s_nop 0
	global_load_lds_dwordx4 v[154:155], off
	s_waitcnt vmcnt(8)
	s_waitcnt lgkmcnt(0)
	s_barrier
	v_mfma_f32_16x16x32_bf16 v[132:135], v[150:153], v[218:221], v[132:135]
	v_mfma_f32_16x16x32_bf16 v[128:131], v[170:173], v[218:221], v[128:131]
	v_mfma_f32_16x16x32_bf16 v[124:127], v[150:153], v[226:229], v[124:127]
	v_mfma_f32_16x16x32_bf16 v[120:123], v[170:173], v[226:229], v[120:123]
	v_mfma_f32_16x16x32_bf16 v[106:109], v[150:153], v[234:237], v[106:109]
	v_mfma_f32_16x16x32_bf16 v[98:101], v[170:173], v[234:237], v[98:101]
	v_mfma_f32_16x16x32_bf16 v[90:93], v[150:153], v[242:245], v[90:93]
	v_mfma_f32_16x16x32_bf16 v[82:85], v[170:173], v[242:245], v[82:85]
	v_mfma_f32_16x16x32_bf16 v[132:135], v[158:161], v[222:225], v[132:135]
	v_mfma_f32_16x16x32_bf16 v[128:131], v[184:187], v[222:225], v[128:131]
	v_mfma_f32_16x16x32_bf16 v[124:127], v[158:161], v[230:233], v[124:127]
	v_mfma_f32_16x16x32_bf16 v[120:123], v[184:187], v[230:233], v[120:123]
	v_mfma_f32_16x16x32_bf16 v[106:109], v[158:161], v[238:241], v[106:109]
	v_mfma_f32_16x16x32_bf16 v[98:101], v[184:187], v[238:241], v[98:101]
	v_mfma_f32_16x16x32_bf16 v[90:93], v[158:161], v[246:249], v[90:93]
	v_mfma_f32_16x16x32_bf16 v[82:85], v[184:187], v[246:249], v[82:85]
	v_mfma_f32_16x16x32_bf16 v[116:119], v[188:191], v[218:221], v[116:119]
	v_mfma_f32_16x16x32_bf16 v[102:105], v[196:199], v[218:221], v[102:105]
	v_mfma_f32_16x16x32_bf16 v[94:97], v[188:191], v[226:229], v[94:97]
	v_mfma_f32_16x16x32_bf16 v[86:89], v[196:199], v[226:229], v[86:89]
	v_mfma_f32_16x16x32_bf16 v[78:81], v[188:191], v[234:237], v[78:81]
	v_mfma_f32_16x16x32_bf16 v[74:77], v[196:199], v[234:237], v[74:77]
	v_mfma_f32_16x16x32_bf16 v[70:73], v[188:191], v[242:245], v[70:73]
	v_mfma_f32_16x16x32_bf16 v[66:69], v[196:199], v[242:245], v[66:69]
	v_mfma_f32_16x16x32_bf16 v[116:119], v[192:195], v[222:225], v[116:119]
	v_mfma_f32_16x16x32_bf16 v[102:105], v[214:217], v[222:225], v[102:105]
	v_mfma_f32_16x16x32_bf16 v[94:97], v[192:195], v[230:233], v[94:97]
	v_mfma_f32_16x16x32_bf16 v[86:89], v[214:217], v[230:233], v[86:89]
	v_mfma_f32_16x16x32_bf16 v[78:81], v[192:195], v[238:241], v[78:81]
	v_mfma_f32_16x16x32_bf16 v[74:77], v[214:217], v[238:241], v[74:77]
	v_mfma_f32_16x16x32_bf16 v[70:73], v[192:195], v[246:249], v[70:73]
	v_mfma_f32_16x16x32_bf16 v[66:69], v[214:217], v[246:249], v[66:69]
	s_barrier
	s_add_i32 s72, s73, s37
	v_lshl_add_u64 v[154:155], s[8:9], 0, v[136:137]
	s_mov_b32 m0, s72
	ds_read_b128 v[218:221], v156 offset:16384
	ds_read_b128 v[222:225], v156 offset:17408
	ds_read_b128 v[226:229], v156 offset:18432
	ds_read_b128 v[230:233], v156 offset:19456
	ds_read_b128 v[234:237], v156 offset:20480
	ds_read_b128 v[238:241], v156 offset:21504
	ds_read_b128 v[242:245], v156 offset:22528
	ds_read_b128 v[246:249], v156 offset:23552
	global_load_lds_dwordx4 v[154:155], off
	s_add_i32 m0, s72, 0x2000
	s_add_u32 s72, s8, 0x200000
	v_lshl_add_u64 v[162:163], s[8:9], 0, v[140:141]
	s_addc_u32 s73, s9, 0
	s_add_i32 s74, s74, s37
	global_load_lds_dwordx4 v[162:163], off
	v_lshl_add_u64 v[200:201], s[72:73], 0, v[136:137]
	s_mov_b32 m0, s74
	v_lshl_add_u64 v[206:207], s[92:93], 0, v[138:139]
	global_load_lds_dwordx4 v[200:201], off
	v_lshl_add_u64 v[200:201], s[72:73], 0, v[140:141]
	s_add_i32 m0, s74, 0x2000
	s_nop 0
	global_load_lds_dwordx4 v[200:201], off
	v_lshl_add_u64 v[200:201], s[92:93], 0, v[110:111]
	s_mov_b32 m0, s17
	s_nop 0
	global_load_lds_dwordx4 v[200:201], off
	s_mov_b32 m0, s57
	s_nop 0
	global_load_lds_dwordx4 v[206:207], off
	s_waitcnt vmcnt(8)
	s_waitcnt lgkmcnt(0)
	s_barrier
	v_mfma_f32_16x16x32_bf16 v[62:65], v[150:153], v[218:221], v[62:65]
	v_mfma_f32_16x16x32_bf16 v[58:61], v[170:173], v[218:221], v[58:61]
	v_mfma_f32_16x16x32_bf16 v[54:57], v[150:153], v[226:229], v[54:57]
	v_mfma_f32_16x16x32_bf16 v[50:53], v[170:173], v[226:229], v[50:53]
	v_mfma_f32_16x16x32_bf16 v[42:45], v[150:153], v[234:237], v[42:45]
	v_mfma_f32_16x16x32_bf16 v[34:37], v[170:173], v[234:237], v[34:37]
	v_mfma_f32_16x16x32_bf16 v[26:29], v[150:153], v[242:245], v[26:29]
	v_mfma_f32_16x16x32_bf16 v[18:21], v[170:173], v[242:245], v[18:21]
	v_mfma_f32_16x16x32_bf16 v[62:65], v[158:161], v[222:225], v[62:65]
	v_mfma_f32_16x16x32_bf16 v[58:61], v[184:187], v[222:225], v[58:61]
	v_mfma_f32_16x16x32_bf16 v[54:57], v[158:161], v[230:233], v[54:57]
	v_mfma_f32_16x16x32_bf16 v[50:53], v[184:187], v[230:233], v[50:53]
	v_mfma_f32_16x16x32_bf16 v[42:45], v[158:161], v[238:241], v[42:45]
	v_mfma_f32_16x16x32_bf16 v[34:37], v[184:187], v[238:241], v[34:37]
	v_mfma_f32_16x16x32_bf16 v[26:29], v[158:161], v[246:249], v[26:29]
	v_mfma_f32_16x16x32_bf16 v[18:21], v[184:187], v[246:249], v[18:21]
	v_mfma_f32_16x16x32_bf16 v[46:49], v[188:191], v[218:221], v[46:49]
	v_mfma_f32_16x16x32_bf16 v[38:41], v[196:199], v[218:221], v[38:41]
	v_mfma_f32_16x16x32_bf16 v[30:33], v[188:191], v[226:229], v[30:33]
	v_mfma_f32_16x16x32_bf16 v[22:25], v[196:199], v[226:229], v[22:25]
	v_mfma_f32_16x16x32_bf16 v[14:17], v[188:191], v[234:237], v[14:17]
	v_mfma_f32_16x16x32_bf16 v[10:13], v[196:199], v[234:237], v[10:13]
	v_mfma_f32_16x16x32_bf16 v[6:9], v[188:191], v[242:245], v[6:9]
	v_mfma_f32_16x16x32_bf16 v[2:5], v[196:199], v[242:245], v[2:5]
	v_mfma_f32_16x16x32_bf16 v[46:49], v[192:195], v[222:225], v[46:49]
	v_mfma_f32_16x16x32_bf16 v[38:41], v[214:217], v[222:225], v[38:41]
	v_mfma_f32_16x16x32_bf16 v[30:33], v[192:195], v[230:233], v[30:33]
	v_mfma_f32_16x16x32_bf16 v[22:25], v[214:217], v[230:233], v[22:25]
	v_mfma_f32_16x16x32_bf16 v[14:17], v[192:195], v[238:241], v[14:17]
	v_mfma_f32_16x16x32_bf16 v[10:13], v[214:217], v[238:241], v[10:13]
	v_mfma_f32_16x16x32_bf16 v[6:9], v[192:195], v[246:249], v[6:9]
	v_mfma_f32_16x16x32_bf16 v[2:5], v[214:217], v[246:249], v[2:5]
	s_barrier
	s_add_i32 s74, 0, 0x18000
	v_add_u32_e32 v157, s74, v1
	s_add_i32 s75, 0, 0x1c000
	ds_read_b128 v[150:153], v157
	ds_read_b128 v[158:161], v157 offset:1024
	ds_read_b128 v[170:173], v157 offset:2048
	ds_read_b128 v[184:187], v157 offset:3072
	v_add_u32_e32 v157, s75, v1
	ds_read_b128 v[188:191], v157
	ds_read_b128 v[192:195], v157 offset:1024
	ds_read_b128 v[196:199], v157 offset:2048
	ds_read_b128 v[214:217], v157 offset:3072
	s_add_u32 s72, s92, 0x200000
	s_addc_u32 s73, s93, 0
	s_mov_b32 m0, s58
	v_lshl_add_u64 v[250:251], s[72:73], 0, v[110:111]
	ds_read_b128 v[218:221], v156 offset:32768
	ds_read_b128 v[222:225], v156 offset:33792
	ds_read_b128 v[226:229], v156 offset:34816
	ds_read_b128 v[230:233], v156 offset:35840
	ds_read_b128 v[234:237], v156 offset:36864
	ds_read_b128 v[238:241], v156 offset:37888
	ds_read_b128 v[242:245], v156 offset:38912
	ds_read_b128 v[246:249], v156 offset:39936
	global_load_lds_dwordx4 v[250:251], off
	v_lshl_add_u64 v[250:251], s[72:73], 0, v[138:139]
	s_mov_b32 m0, s59
	s_nop 0
	global_load_lds_dwordx4 v[250:251], off
	s_waitcnt vmcnt(8)
	s_waitcnt lgkmcnt(0)
	s_barrier
	v_mfma_f32_16x16x32_bf16 v[132:135], v[150:153], v[218:221], v[132:135]
	v_mfma_f32_16x16x32_bf16 v[128:131], v[170:173], v[218:221], v[128:131]
	v_mfma_f32_16x16x32_bf16 v[124:127], v[150:153], v[226:229], v[124:127]
	v_mfma_f32_16x16x32_bf16 v[120:123], v[170:173], v[226:229], v[120:123]
	v_mfma_f32_16x16x32_bf16 v[106:109], v[150:153], v[234:237], v[106:109]
	v_mfma_f32_16x16x32_bf16 v[98:101], v[170:173], v[234:237], v[98:101]
	v_mfma_f32_16x16x32_bf16 v[90:93], v[150:153], v[242:245], v[90:93]
	v_mfma_f32_16x16x32_bf16 v[82:85], v[170:173], v[242:245], v[82:85]
	v_mfma_f32_16x16x32_bf16 v[132:135], v[158:161], v[222:225], v[132:135]
	v_mfma_f32_16x16x32_bf16 v[128:131], v[184:187], v[222:225], v[128:131]
	v_mfma_f32_16x16x32_bf16 v[124:127], v[158:161], v[230:233], v[124:127]
	v_mfma_f32_16x16x32_bf16 v[120:123], v[184:187], v[230:233], v[120:123]
	v_mfma_f32_16x16x32_bf16 v[106:109], v[158:161], v[238:241], v[106:109]
	v_mfma_f32_16x16x32_bf16 v[98:101], v[184:187], v[238:241], v[98:101]
	v_mfma_f32_16x16x32_bf16 v[90:93], v[158:161], v[246:249], v[90:93]
	v_mfma_f32_16x16x32_bf16 v[82:85], v[184:187], v[246:249], v[82:85]
	v_mfma_f32_16x16x32_bf16 v[116:119], v[188:191], v[218:221], v[116:119]
	v_mfma_f32_16x16x32_bf16 v[102:105], v[196:199], v[218:221], v[102:105]
	v_mfma_f32_16x16x32_bf16 v[94:97], v[188:191], v[226:229], v[94:97]
	v_mfma_f32_16x16x32_bf16 v[86:89], v[196:199], v[226:229], v[86:89]
	v_mfma_f32_16x16x32_bf16 v[78:81], v[188:191], v[234:237], v[78:81]
	v_mfma_f32_16x16x32_bf16 v[74:77], v[196:199], v[234:237], v[74:77]
	v_mfma_f32_16x16x32_bf16 v[70:73], v[188:191], v[242:245], v[70:73]
	v_mfma_f32_16x16x32_bf16 v[66:69], v[196:199], v[242:245], v[66:69]
	v_mfma_f32_16x16x32_bf16 v[116:119], v[192:195], v[222:225], v[116:119]
	v_mfma_f32_16x16x32_bf16 v[102:105], v[214:217], v[222:225], v[102:105]
	v_mfma_f32_16x16x32_bf16 v[94:97], v[192:195], v[230:233], v[94:97]
	v_mfma_f32_16x16x32_bf16 v[86:89], v[214:217], v[230:233], v[86:89]
	v_mfma_f32_16x16x32_bf16 v[78:81], v[192:195], v[238:241], v[78:81]
	v_mfma_f32_16x16x32_bf16 v[74:77], v[214:217], v[238:241], v[74:77]
	v_mfma_f32_16x16x32_bf16 v[70:73], v[192:195], v[246:249], v[70:73]
	v_mfma_f32_16x16x32_bf16 v[66:69], v[214:217], v[246:249], v[66:69]
	s_barrier
	s_add_i32 s72, s74, s37
	v_lshl_add_u64 v[154:155], v[154:155], 0, s[26:27]
	s_mov_b32 m0, s72
	ds_read_b128 v[218:221], v156 offset:49152
	ds_read_b128 v[222:225], v156 offset:50176
	ds_read_b128 v[226:229], v156 offset:51200
	ds_read_b128 v[230:233], v156 offset:52224
	ds_read_b128 v[234:237], v156 offset:53248
	ds_read_b128 v[238:241], v156 offset:54272
	ds_read_b128 v[242:245], v156 offset:55296
	ds_read_b128 v[246:249], v156 offset:56320
	global_load_lds_dwordx4 v[154:155], off
	s_add_i32 m0, s72, 0x2000
	s_add_u32 s8, s8, 0x200080
	v_lshl_add_u64 v[154:155], v[162:163], 0, s[26:27]
	s_addc_u32 s9, s9, 0
	s_add_i32 s72, s75, s37
	global_load_lds_dwordx4 v[154:155], off
	v_lshl_add_u64 v[154:155], s[8:9], 0, v[136:137]
	s_mov_b32 m0, s72
	s_nop 0
	global_load_lds_dwordx4 v[154:155], off
	v_lshl_add_u64 v[154:155], s[8:9], 0, v[140:141]
	s_add_i32 m0, s72, 0x2000
	s_nop 0
	global_load_lds_dwordx4 v[154:155], off
	v_lshl_add_u64 v[154:155], v[200:201], 0, s[26:27]
	s_mov_b32 m0, s61
	s_nop 0
	global_load_lds_dwordx4 v[154:155], off
	v_lshl_add_u64 v[154:155], v[206:207], 0, s[26:27]
	s_mov_b32 m0, s62
	s_nop 0
	global_load_lds_dwordx4 v[154:155], off
	s_waitcnt vmcnt(8)
	s_waitcnt lgkmcnt(0)
	s_barrier
	v_mfma_f32_16x16x32_bf16 v[62:65], v[150:153], v[218:221], v[62:65]
	v_mfma_f32_16x16x32_bf16 v[58:61], v[170:173], v[218:221], v[58:61]
	v_mfma_f32_16x16x32_bf16 v[54:57], v[150:153], v[226:229], v[54:57]
	v_mfma_f32_16x16x32_bf16 v[50:53], v[170:173], v[226:229], v[50:53]
	v_mfma_f32_16x16x32_bf16 v[42:45], v[150:153], v[234:237], v[42:45]
	v_mfma_f32_16x16x32_bf16 v[34:37], v[170:173], v[234:237], v[34:37]
	v_mfma_f32_16x16x32_bf16 v[26:29], v[150:153], v[242:245], v[26:29]
	v_mfma_f32_16x16x32_bf16 v[18:21], v[170:173], v[242:245], v[18:21]
	v_mfma_f32_16x16x32_bf16 v[62:65], v[158:161], v[222:225], v[62:65]
	v_mfma_f32_16x16x32_bf16 v[58:61], v[184:187], v[222:225], v[58:61]
	v_mfma_f32_16x16x32_bf16 v[54:57], v[158:161], v[230:233], v[54:57]
	v_mfma_f32_16x16x32_bf16 v[50:53], v[184:187], v[230:233], v[50:53]
	v_mfma_f32_16x16x32_bf16 v[42:45], v[158:161], v[238:241], v[42:45]
	v_mfma_f32_16x16x32_bf16 v[34:37], v[184:187], v[238:241], v[34:37]
	v_mfma_f32_16x16x32_bf16 v[26:29], v[158:161], v[246:249], v[26:29]
	v_mfma_f32_16x16x32_bf16 v[18:21], v[184:187], v[246:249], v[18:21]
	v_mfma_f32_16x16x32_bf16 v[46:49], v[188:191], v[218:221], v[46:49]
	v_mfma_f32_16x16x32_bf16 v[38:41], v[196:199], v[218:221], v[38:41]
	v_mfma_f32_16x16x32_bf16 v[30:33], v[188:191], v[226:229], v[30:33]
	v_mfma_f32_16x16x32_bf16 v[22:25], v[196:199], v[226:229], v[22:25]
	v_mfma_f32_16x16x32_bf16 v[14:17], v[188:191], v[234:237], v[14:17]
	v_mfma_f32_16x16x32_bf16 v[10:13], v[196:199], v[234:237], v[10:13]
	v_mfma_f32_16x16x32_bf16 v[6:9], v[188:191], v[242:245], v[6:9]
	v_mfma_f32_16x16x32_bf16 v[2:5], v[196:199], v[242:245], v[2:5]
	v_mfma_f32_16x16x32_bf16 v[46:49], v[192:195], v[222:225], v[46:49]
	v_mfma_f32_16x16x32_bf16 v[38:41], v[214:217], v[222:225], v[38:41]
	v_mfma_f32_16x16x32_bf16 v[30:33], v[192:195], v[230:233], v[30:33]
	v_mfma_f32_16x16x32_bf16 v[22:25], v[214:217], v[230:233], v[22:25]
	v_mfma_f32_16x16x32_bf16 v[14:17], v[192:195], v[238:241], v[14:17]
	v_mfma_f32_16x16x32_bf16 v[10:13], v[214:217], v[238:241], v[10:13]
	v_mfma_f32_16x16x32_bf16 v[6:9], v[192:195], v[246:249], v[6:9]
	v_mfma_f32_16x16x32_bf16 v[2:5], v[214:217], v[246:249], v[2:5]
	s_barrier
	s_add_u32 s86, s86, 0x100
	s_addc_u32 s87, s87, 0
	s_add_u32 s69, s69, 0x100
	s_addc_u32 s70, s70, 0
	s_cmp_ge_u32 s71, s66
	s_mov_b32 s8, s71
	s_cbranch_scc0 .LBB0_853
	s_and_b64 vcc, exec, s[42:43]
	s_cbranch_vccz .LBB0_856
	s_barrier

.LBB0_879:
	s_setprio 0
	s_waitcnt vmcnt(0)
	v_readlane_b32 s86, v254, 61
	v_readlane_b32 s84, v255, 0
	v_readlane_b32 s58, v255, 2
	v_readlane_b32 s60, v255, 4
	v_readlane_b32 s62, v255, 6
	v_readlane_b32 s54, v255, 10
	v_readlane_b32 s64, v255, 12
	v_readlane_b32 s46, v254, 55
	v_readlane_b32 s72, v254, 59
	v_readlane_b32 s73, v254, 60
	v_readlane_b32 s87, v254, 62
	v_readlane_b32 s74, v254, 63
	v_readlane_b32 s85, v255, 1
	v_readlane_b32 s59, v255, 3
	v_readlane_b32 s61, v255, 5
	v_readlane_b32 s63, v255, 7
	v_readlane_b32 s55, v255, 11
	v_readlane_b32 s65, v255, 13
	v_readlane_b32 s47, v254, 56
	s_barrier
